# plus: removed the 24 provably redundant s_waitcnt lgkmcnt(0) that directly follow the identical wait+s_barrier in the GEMM K-loops
# speedup vs baseline: 1.0039x; 1.0039x over previous
; #define PG8_STAGE(bufoff, gbase, voff) do { _Pragma("unroll") for (int _i = 0; _i < 2; ++_i) \
;         __builtin_amdgcn_global_load_lds((const unsigned*)((const char*)(gbase) + (voff)[_i]), (PG8_LAS unsigned*)(lds + (bufoff) + ldsw + _i * 8192), 16, 0, 0); } while (0)
; #define PG8_LDA(dst, b, h) do { _Pragma("unroll") for (int m = 0; m < 4; ++m) _Pragma("unroll") for (int k = 0; k < 2; ++k) dst[m][k] = *(const PG8_LAS bf16x8*)(lds + PG8_SA(b, h) + aoff + m * 2048 + k * 1024); } while (0)
; #define PG8_LDB(dst, b, h) do { _Pragma("unroll") for (int n = 0; n < 2; ++n) _Pragma("unroll") for (int k = 0; k < 2; ++k) dst[n][k] = *(const PG8_LAS bf16x8*)(lds + PG8_SB(b, h) + boff + n * 2048 + k * 1024); } while (0)
; #define PG8_MMA(ai, bj, At, Bt) do { __builtin_amdgcn_s_setprio(1); _Pragma("unroll") for (int m = 0; m < 4; ++m) _Pragma("unroll") for (int n = 0; n < 2; ++n) _Pragma("unroll") for (int k = 0; k < 2; ++k) \
;         acc[ai][bj][m][n] = __builtin_amdgcn_mfma_f32_16x16x32_bf16(Bt[n][k], At[m][k], acc[ai][bj][m][n], 0, 0, 0); __builtin_amdgcn_s_setprio(0); } while (0)
; #define PG8_WAIT_V(n) asm volatile("s_waitcnt vmcnt(" #n ")" ::: "memory")
; #define PG8_WAIT_L(n) asm volatile("s_waitcnt lgkmcnt(" #n ")" ::: "memory")
; #define PG8_BAR __builtin_amdgcn_s_barrier()
; #define PG8_SCHED __builtin_amdgcn_sched_barrier(0)
; template <class Epi, class Sched, bool ALIGN_EPI = false, bool SP2 = false>
; __device__ __forceinline__ void gemm_phase(PG8_LAS unsigned char* lds, const Gemm g, const Sched& S, const Epi& E, const int tid) {
;     ...
;             const bool last = (t == nt - 2);
;             const char* a1 = cA + (size_t)(t + 1) * kstep;
;             const char* a2 = last ? nA : cA + (size_t)(t + 2) * kstep; const char* b2 = last ? nB : cB + (size_t)(t + 2) * kstep;
;             const char* a3 = a2 + kstep; const char* b3 = b2 + kstep;
;             if (last && has_next) S.a_ready(nxt);
;             if constexpr (SP2) {
;             PG8_LDB(B0, 0, 0); PG8_LDB(B1, 0, 1); PG8_SCHED; PG8_LDA(At, 0, 0); PG8_STAGE(PG8_SA(1, 1), a1 + hstepA, voffA);
;             PG8_WAIT_V(8); PG8_WAIT_L(0); PG8_BAR; PG8_MMA(0, 0, At, B0); PG8_MMA(0, 1, At, B1); PG8_BAR; PG8_SCHED;
;             PG8_LDA(At, 0, 1); PG8_STAGE(PG8_SB(0, 0), b2, voffB); PG8_STAGE(PG8_SB(0, 1), b2 + hstepB, voffB); PG8_STAGE(PG8_SA(0, 0), a2, voffA);
.LBB0_36:
	s_add_u32 s24, s46, 0xfffc0080
	s_addc_u32 s25, s47, -1
	s_add_i32 s63, 0, 0x10000
	s_cmp_eq_u32 s59, 12
	s_cselect_b32 s51, s19, s25
	s_cselect_b32 s50, s53, s24
	s_cselect_b32 s49, s15, s58
	s_cselect_b32 s48, s54, s55
	s_add_i32 s65, 0, 0x14000
	v_add_u32_e32 v154, s63, v143
	v_add_u32_e32 v170, s65, v143
	ds_read_b128 v[138:141], v154
	ds_read_b128 v[146:149], v154 offset:1024
	ds_read_b128 v[150:153], v154 offset:2048
	ds_read_b128 v[154:157], v154 offset:3072
	ds_read_b128 v[158:161], v170
	ds_read_b128 v[162:165], v170 offset:1024
	ds_read_b128 v[166:169], v170 offset:2048
	ds_read_b128 v[170:173], v170 offset:3072
	v_lshl_add_u64 v[190:191], s[46:47], 0, v[136:137]
	s_add_i32 m0, s23, 0xc000
	ds_read_b128 v[174:177], v145
	ds_read_b128 v[178:181], v145 offset:1024
	ds_read_b128 v[182:185], v145 offset:2048
	ds_read_b128 v[186:189], v145 offset:3072
	ds_read_b128 v[200:203], v145 offset:4096
	ds_read_b128 v[204:207], v145 offset:5120
	ds_read_b128 v[208:211], v145 offset:6144
	ds_read_b128 v[212:215], v145 offset:7168
	global_load_lds_dwordx4 v[190:191], off
	v_lshl_add_u64 v[190:191], s[46:47], 0, v[134:135]
	s_add_i32 m0, s23, 0xe000
	s_nop 0
	global_load_lds_dwordx4 v[190:191], off
	s_waitcnt vmcnt(8)
	s_waitcnt lgkmcnt(0)
	s_barrier
	s_setprio 1
	v_mfma_f32_16x16x32_bf16 v[124:127], v[138:141], v[174:177], v[124:127]
	v_mfma_f32_16x16x32_bf16 v[120:123], v[150:153], v[174:177], v[120:123]
	v_mfma_f32_16x16x32_bf16 v[108:111], v[138:141], v[182:185], v[108:111]
	v_mfma_f32_16x16x32_bf16 v[104:107], v[150:153], v[182:185], v[104:107]
	v_mfma_f32_16x16x32_bf16 v[92:95], v[138:141], v[200:203], v[92:95]
	v_mfma_f32_16x16x32_bf16 v[88:91], v[150:153], v[200:203], v[88:91]
	v_mfma_f32_16x16x32_bf16 v[76:79], v[138:141], v[208:211], v[76:79]
	v_mfma_f32_16x16x32_bf16 v[72:75], v[150:153], v[208:211], v[72:75]
	v_mfma_f32_16x16x32_bf16 v[124:127], v[146:149], v[178:181], v[124:127]
	v_mfma_f32_16x16x32_bf16 v[120:123], v[154:157], v[178:181], v[120:123]
	v_mfma_f32_16x16x32_bf16 v[108:111], v[146:149], v[186:189], v[108:111]
	v_mfma_f32_16x16x32_bf16 v[104:107], v[154:157], v[186:189], v[104:107]
	v_mfma_f32_16x16x32_bf16 v[92:95], v[146:149], v[204:207], v[92:95]
	v_mfma_f32_16x16x32_bf16 v[88:91], v[154:157], v[204:207], v[88:91]
	v_mfma_f32_16x16x32_bf16 v[76:79], v[146:149], v[212:215], v[76:79]
	v_mfma_f32_16x16x32_bf16 v[72:75], v[154:157], v[212:215], v[72:75]
	s_setprio 0
	s_setprio 1
	v_mfma_f32_16x16x32_bf16 v[116:119], v[158:161], v[174:177], v[116:119]
	v_mfma_f32_16x16x32_bf16 v[112:115], v[166:169], v[174:177], v[112:115]
	v_mfma_f32_16x16x32_bf16 v[100:103], v[158:161], v[182:185], v[100:103]
	v_mfma_f32_16x16x32_bf16 v[96:99], v[166:169], v[182:185], v[96:99]
	v_mfma_f32_16x16x32_bf16 v[84:87], v[158:161], v[200:203], v[84:87]
	v_mfma_f32_16x16x32_bf16 v[80:83], v[166:169], v[200:203], v[80:83]
	v_mfma_f32_16x16x32_bf16 v[68:71], v[158:161], v[208:211], v[68:71]
	v_mfma_f32_16x16x32_bf16 v[64:67], v[166:169], v[208:211], v[64:67]
	v_mfma_f32_16x16x32_bf16 v[116:119], v[162:165], v[178:181], v[116:119]
	v_mfma_f32_16x16x32_bf16 v[112:115], v[170:173], v[178:181], v[112:115]
	v_mfma_f32_16x16x32_bf16 v[100:103], v[162:165], v[186:189], v[100:103]
	v_mfma_f32_16x16x32_bf16 v[96:99], v[170:173], v[186:189], v[96:99]
	v_mfma_f32_16x16x32_bf16 v[84:87], v[162:165], v[204:207], v[84:87]
	v_mfma_f32_16x16x32_bf16 v[80:83], v[170:173], v[204:207], v[80:83]
	v_mfma_f32_16x16x32_bf16 v[68:71], v[162:165], v[212:215], v[68:71]
	v_mfma_f32_16x16x32_bf16 v[64:67], v[170:173], v[212:215], v[64:67]
	s_setprio 0
	s_barrier
	s_add_i32 s24, s63, s21
	v_lshl_add_u64 v[190:191], s[48:49], 0, v[192:193]
	s_mov_b32 m0, s24
	ds_read_b128 v[174:177], v145 offset:16384
	ds_read_b128 v[178:181], v145 offset:17408
	ds_read_b128 v[182:185], v145 offset:18432
	ds_read_b128 v[186:189], v145 offset:19456
	ds_read_b128 v[200:203], v145 offset:20480
	ds_read_b128 v[204:207], v145 offset:21504
	ds_read_b128 v[208:211], v145 offset:22528
	ds_read_b128 v[212:215], v145 offset:23552
	global_load_lds_dwordx4 v[190:191], off
	s_add_i32 m0, s24, 0x2000
	s_add_u32 s24, s48, 0x40000
	v_lshl_add_u64 v[216:217], s[48:49], 0, v[128:129]
	s_addc_u32 s25, s49, 0
	s_add_i32 s63, s65, s21
	global_load_lds_dwordx4 v[216:217], off
	v_lshl_add_u64 v[218:219], s[24:25], 0, v[192:193]
	s_mov_b32 m0, s63
	v_lshl_add_u64 v[220:221], s[50:51], 0, v[130:131]
	global_load_lds_dwordx4 v[218:219], off
	v_lshl_add_u64 v[218:219], s[24:25], 0, v[128:129]
	s_add_i32 m0, s63, 0x2000
	s_nop 0
	global_load_lds_dwordx4 v[218:219], off
	v_lshl_add_u64 v[218:219], s[50:51], 0, v[132:133]
	s_mov_b32 m0, s23
	s_nop 0
	global_load_lds_dwordx4 v[218:219], off
	s_mov_b32 m0, s26
	s_nop 0
	global_load_lds_dwordx4 v[220:221], off
	s_waitcnt vmcnt(8)
	s_waitcnt lgkmcnt(0)
	s_barrier
; #define PG8_STAGE(bufoff, gbase, voff) do { _Pragma("unroll") for (int _i = 0; _i < 2; ++_i) \
;         __builtin_amdgcn_global_load_lds((const unsigned*)((const char*)(gbase) + (voff)[_i]), (PG8_LAS unsigned*)(lds + (bufoff) + ldsw + _i * 8192), 16, 0, 0); } while (0)
; #define PG8_LDA(dst, b, h) do { _Pragma("unroll") for (int m = 0; m < 4; ++m) _Pragma("unroll") for (int k = 0; k < 2; ++k) dst[m][k] = *(const PG8_LAS bf16x8*)(lds + PG8_SA(b, h) + aoff + m * 2048 + k * 1024); } while (0)
; #define PG8_LDB(dst, b, h) do { _Pragma("unroll") for (int n = 0; n < 2; ++n) _Pragma("unroll") for (int k = 0; k < 2; ++k) dst[n][k] = *(const PG8_LAS bf16x8*)(lds + PG8_SB(b, h) + boff + n * 2048 + k * 1024); } while (0)
; #define PG8_MMA(ai, bj, At, Bt) do { __builtin_amdgcn_s_setprio(1); _Pragma("unroll") for (int m = 0; m < 4; ++m) _Pragma("unroll") for (int n = 0; n < 2; ++n) _Pragma("unroll") for (int k = 0; k < 2; ++k) \
;         acc[ai][bj][m][n] = __builtin_amdgcn_mfma_f32_16x16x32_bf16(Bt[n][k], At[m][k], acc[ai][bj][m][n], 0, 0, 0); __builtin_amdgcn_s_setprio(0); } while (0)
; #define PG8_WAIT_V(n) asm volatile("s_waitcnt vmcnt(" #n ")" ::: "memory")
; #define PG8_WAIT_L(n) asm volatile("s_waitcnt lgkmcnt(" #n ")" ::: "memory")
; #define PG8_BAR __builtin_amdgcn_s_barrier()
; #define PG8_SCHED __builtin_amdgcn_sched_barrier(0)
; template <class Epi, class Sched, bool ALIGN_EPI = false, bool SP2 = false>
; __device__ __forceinline__ void gemm_phase(PG8_LAS unsigned char* lds, const Gemm g, const Sched& S, const Epi& E, const int tid) {
;     ...
;             PG8_WAIT_V(8); PG8_WAIT_L(0); PG8_BAR; PG8_MMA(1, 0, At, B0); PG8_MMA(1, 1, At, B1); PG8_BAR; PG8_SCHED;
;             PG8_LDB(B0, 1, 0); PG8_LDB(B1, 1, 1); PG8_SCHED; PG8_LDA(At, 1, 0); PG8_STAGE(PG8_SA(0, 1), a2 + hstepA, voffA);
;             PG8_WAIT_V(8); PG8_WAIT_L(0); PG8_BAR; PG8_MMA(0, 0, At, B0); PG8_MMA(0, 1, At, B1); PG8_BAR; PG8_SCHED;
	s_setprio 1
	v_mfma_f32_16x16x32_bf16 v[60:63], v[138:141], v[174:177], v[60:63]
	v_mfma_f32_16x16x32_bf16 v[56:59], v[150:153], v[174:177], v[56:59]
	v_mfma_f32_16x16x32_bf16 v[44:47], v[138:141], v[182:185], v[44:47]
	v_mfma_f32_16x16x32_bf16 v[40:43], v[150:153], v[182:185], v[40:43]
	v_mfma_f32_16x16x32_bf16 v[28:31], v[138:141], v[200:203], v[28:31]
	v_mfma_f32_16x16x32_bf16 v[24:27], v[150:153], v[200:203], v[24:27]
	v_mfma_f32_16x16x32_bf16 v[12:15], v[138:141], v[208:211], v[12:15]
	v_mfma_f32_16x16x32_bf16 v[8:11], v[150:153], v[208:211], v[8:11]
	v_mfma_f32_16x16x32_bf16 v[60:63], v[146:149], v[178:181], v[60:63]
	v_mfma_f32_16x16x32_bf16 v[56:59], v[154:157], v[178:181], v[56:59]
	v_mfma_f32_16x16x32_bf16 v[44:47], v[146:149], v[186:189], v[44:47]
	v_mfma_f32_16x16x32_bf16 v[40:43], v[154:157], v[186:189], v[40:43]
	v_mfma_f32_16x16x32_bf16 v[28:31], v[146:149], v[204:207], v[28:31]
	v_mfma_f32_16x16x32_bf16 v[24:27], v[154:157], v[204:207], v[24:27]
	v_mfma_f32_16x16x32_bf16 v[12:15], v[146:149], v[212:215], v[12:15]
	v_mfma_f32_16x16x32_bf16 v[8:11], v[154:157], v[212:215], v[8:11]
	s_setprio 0
	s_setprio 1
	v_mfma_f32_16x16x32_bf16 v[52:55], v[158:161], v[174:177], v[52:55]
	v_mfma_f32_16x16x32_bf16 v[48:51], v[166:169], v[174:177], v[48:51]
	v_mfma_f32_16x16x32_bf16 v[36:39], v[158:161], v[182:185], v[36:39]
	v_mfma_f32_16x16x32_bf16 v[32:35], v[166:169], v[182:185], v[32:35]
	v_mfma_f32_16x16x32_bf16 v[20:23], v[158:161], v[200:203], v[20:23]
	v_mfma_f32_16x16x32_bf16 v[16:19], v[166:169], v[200:203], v[16:19]
	v_mfma_f32_16x16x32_bf16 v[4:7], v[158:161], v[208:211], v[4:7]
	v_mfma_f32_16x16x32_bf16 v[0:3], v[166:169], v[208:211], v[0:3]
	v_mfma_f32_16x16x32_bf16 v[52:55], v[162:165], v[178:181], v[52:55]
	v_mfma_f32_16x16x32_bf16 v[48:51], v[170:173], v[178:181], v[48:51]
	v_mfma_f32_16x16x32_bf16 v[36:39], v[162:165], v[186:189], v[36:39]
	v_mfma_f32_16x16x32_bf16 v[32:35], v[170:173], v[186:189], v[32:35]
	v_mfma_f32_16x16x32_bf16 v[20:23], v[162:165], v[204:207], v[20:23]
	v_mfma_f32_16x16x32_bf16 v[16:19], v[170:173], v[204:207], v[16:19]
	v_mfma_f32_16x16x32_bf16 v[4:7], v[162:165], v[212:215], v[4:7]
	v_mfma_f32_16x16x32_bf16 v[0:3], v[170:173], v[212:215], v[0:3]
	s_setprio 0
	s_barrier
	s_add_i32 s63, 0, 0x18000
	s_add_i32 s65, 0, 0x1c000
	v_add_u32_e32 v154, s63, v143
	v_add_u32_e32 v170, s65, v143
	ds_read_b128 v[138:141], v154
	ds_read_b128 v[146:149], v154 offset:1024
	ds_read_b128 v[150:153], v154 offset:2048
	ds_read_b128 v[154:157], v154 offset:3072
	ds_read_b128 v[158:161], v170
	ds_read_b128 v[162:165], v170 offset:1024
	ds_read_b128 v[166:169], v170 offset:2048
	ds_read_b128 v[170:173], v170 offset:3072
	s_add_u32 s24, s50, 0x40000
	s_addc_u32 s25, s51, 0
	s_mov_b32 m0, s27
	v_lshl_add_u64 v[222:223], s[24:25], 0, v[132:133]
	ds_read_b128 v[174:177], v145 offset:32768
	ds_read_b128 v[178:181], v145 offset:33792
	ds_read_b128 v[182:185], v145 offset:34816
	ds_read_b128 v[186:189], v145 offset:35840
	ds_read_b128 v[200:203], v145 offset:36864
	ds_read_b128 v[204:207], v145 offset:37888
	ds_read_b128 v[208:211], v145 offset:38912
	ds_read_b128 v[212:215], v145 offset:39936
	global_load_lds_dwordx4 v[222:223], off
	v_lshl_add_u64 v[222:223], s[24:25], 0, v[130:131]
	s_mov_b32 m0, s28
	s_nop 0
	global_load_lds_dwordx4 v[222:223], off
	s_waitcnt vmcnt(8)
	s_waitcnt lgkmcnt(0)
	s_barrier
	s_setprio 1
	v_mfma_f32_16x16x32_bf16 v[124:127], v[138:141], v[174:177], v[124:127]
	v_mfma_f32_16x16x32_bf16 v[120:123], v[150:153], v[174:177], v[120:123]
	v_mfma_f32_16x16x32_bf16 v[108:111], v[138:141], v[182:185], v[108:111]
	v_mfma_f32_16x16x32_bf16 v[104:107], v[150:153], v[182:185], v[104:107]
	v_mfma_f32_16x16x32_bf16 v[92:95], v[138:141], v[200:203], v[92:95]
	v_mfma_f32_16x16x32_bf16 v[88:91], v[150:153], v[200:203], v[88:91]
	v_mfma_f32_16x16x32_bf16 v[76:79], v[138:141], v[208:211], v[76:79]
	v_mfma_f32_16x16x32_bf16 v[72:75], v[150:153], v[208:211], v[72:75]
	v_mfma_f32_16x16x32_bf16 v[124:127], v[146:149], v[178:181], v[124:127]
	v_mfma_f32_16x16x32_bf16 v[120:123], v[154:157], v[178:181], v[120:123]
	v_mfma_f32_16x16x32_bf16 v[108:111], v[146:149], v[186:189], v[108:111]
	v_mfma_f32_16x16x32_bf16 v[104:107], v[154:157], v[186:189], v[104:107]
	v_mfma_f32_16x16x32_bf16 v[92:95], v[146:149], v[204:207], v[92:95]
	v_mfma_f32_16x16x32_bf16 v[88:91], v[154:157], v[204:207], v[88:91]
	v_mfma_f32_16x16x32_bf16 v[76:79], v[146:149], v[212:215], v[76:79]
	v_mfma_f32_16x16x32_bf16 v[72:75], v[154:157], v[212:215], v[72:75]
	s_setprio 0
	s_setprio 1
	v_mfma_f32_16x16x32_bf16 v[116:119], v[158:161], v[174:177], v[116:119]
	v_mfma_f32_16x16x32_bf16 v[112:115], v[166:169], v[174:177], v[112:115]
	v_mfma_f32_16x16x32_bf16 v[100:103], v[158:161], v[182:185], v[100:103]
	v_mfma_f32_16x16x32_bf16 v[96:99], v[166:169], v[182:185], v[96:99]
	v_mfma_f32_16x16x32_bf16 v[84:87], v[158:161], v[200:203], v[84:87]
	v_mfma_f32_16x16x32_bf16 v[80:83], v[166:169], v[200:203], v[80:83]
	v_mfma_f32_16x16x32_bf16 v[68:71], v[158:161], v[208:211], v[68:71]
	v_mfma_f32_16x16x32_bf16 v[64:67], v[166:169], v[208:211], v[64:67]
	v_mfma_f32_16x16x32_bf16 v[116:119], v[162:165], v[178:181], v[116:119]
	v_mfma_f32_16x16x32_bf16 v[112:115], v[170:173], v[178:181], v[112:115]
	v_mfma_f32_16x16x32_bf16 v[100:103], v[162:165], v[186:189], v[100:103]
	v_mfma_f32_16x16x32_bf16 v[96:99], v[170:173], v[186:189], v[96:99]
	v_mfma_f32_16x16x32_bf16 v[84:87], v[162:165], v[204:207], v[84:87]
	v_mfma_f32_16x16x32_bf16 v[80:83], v[170:173], v[204:207], v[80:83]
	v_mfma_f32_16x16x32_bf16 v[68:71], v[162:165], v[212:215], v[68:71]
	v_mfma_f32_16x16x32_bf16 v[64:67], v[170:173], v[212:215], v[64:67]
	s_setprio 0
	s_barrier
; #define PG8_STAGE(bufoff, gbase, voff) do { _Pragma("unroll") for (int _i = 0; _i < 2; ++_i) \
;         __builtin_amdgcn_global_load_lds((const unsigned*)((const char*)(gbase) + (voff)[_i]), (PG8_LAS unsigned*)(lds + (bufoff) + ldsw + _i * 8192), 16, 0, 0); } while (0)
; #define PG8_LDA(dst, b, h) do { _Pragma("unroll") for (int m = 0; m < 4; ++m) _Pragma("unroll") for (int k = 0; k < 2; ++k) dst[m][k] = *(const PG8_LAS bf16x8*)(lds + PG8_SA(b, h) + aoff + m * 2048 + k * 1024); } while (0)
; #define PG8_MMA(ai, bj, At, Bt) do { __builtin_amdgcn_s_setprio(1); _Pragma("unroll") for (int m = 0; m < 4; ++m) _Pragma("unroll") for (int n = 0; n < 2; ++n) _Pragma("unroll") for (int k = 0; k < 2; ++k) \
;         acc[ai][bj][m][n] = __builtin_amdgcn_mfma_f32_16x16x32_bf16(Bt[n][k], At[m][k], acc[ai][bj][m][n], 0, 0, 0); __builtin_amdgcn_s_setprio(0); } while (0)
; #define PG8_WAIT_V(n) asm volatile("s_waitcnt vmcnt(" #n ")" ::: "memory")
; #define PG8_WAIT_L(n) asm volatile("s_waitcnt lgkmcnt(" #n ")" ::: "memory")
; #define PG8_BAR __builtin_amdgcn_s_barrier()
; #define PG8_SCHED __builtin_amdgcn_sched_barrier(0)
; template <class Epi, class Sched, bool ALIGN_EPI = false, bool SP2 = false>
; __device__ __forceinline__ void gemm_phase(PG8_LAS unsigned char* lds, const Gemm g, const Sched& S, const Epi& E, const int tid) {
;     ...
;             PG8_LDA(At, 1, 1); PG8_STAGE(PG8_SB(1, 0), b3, voffB); PG8_STAGE(PG8_SB(1, 1), b3 + hstepB, voffB); PG8_STAGE(PG8_SA(1, 0), a3, voffA);
;             PG8_WAIT_V(8); PG8_WAIT_L(0); PG8_BAR; PG8_MMA(1, 0, At, B0); PG8_MMA(1, 1, At, B1); PG8_BAR; PG8_SCHED;
;     ...
;         if constexpr (ALIGN_EPI) { if (wr == 0) PG8_BAR; }
	s_add_i32 s24, s63, s21
	v_lshl_add_u64 v[190:191], v[190:191], 0, s[60:61]
	s_mov_b32 m0, s24
	ds_read_b128 v[174:177], v145 offset:49152
	ds_read_b128 v[178:181], v145 offset:50176
	ds_read_b128 v[182:185], v145 offset:51200
	ds_read_b128 v[186:189], v145 offset:52224
	ds_read_b128 v[200:203], v145 offset:53248
	ds_read_b128 v[204:207], v145 offset:54272
	ds_read_b128 v[208:211], v145 offset:55296
	ds_read_b128 v[212:215], v145 offset:56320
	global_load_lds_dwordx4 v[190:191], off
	s_add_i32 m0, s24, 0x2000
	s_add_u32 s24, s48, 0x40080
	v_lshl_add_u64 v[190:191], v[216:217], 0, s[60:61]
	s_addc_u32 s25, s49, 0
	s_add_i32 s48, s65, s21
	global_load_lds_dwordx4 v[190:191], off
	v_lshl_add_u64 v[190:191], s[24:25], 0, v[192:193]
	s_mov_b32 m0, s48
	s_nop 0
	global_load_lds_dwordx4 v[190:191], off
	v_lshl_add_u64 v[190:191], s[24:25], 0, v[128:129]
	s_add_i32 m0, s48, 0x2000
	s_nop 0
	global_load_lds_dwordx4 v[190:191], off
	v_lshl_add_u64 v[190:191], v[218:219], 0, s[60:61]
	s_mov_b32 m0, s29
	s_nop 0
	global_load_lds_dwordx4 v[190:191], off
	v_lshl_add_u64 v[190:191], v[220:221], 0, s[60:61]
	s_mov_b32 m0, s40
	s_nop 0
	global_load_lds_dwordx4 v[190:191], off
	s_waitcnt vmcnt(8)
	s_waitcnt lgkmcnt(0)
	s_barrier
	s_setprio 1
	v_mfma_f32_16x16x32_bf16 v[60:63], v[138:141], v[174:177], v[60:63]
	v_mfma_f32_16x16x32_bf16 v[56:59], v[150:153], v[174:177], v[56:59]
	v_mfma_f32_16x16x32_bf16 v[44:47], v[138:141], v[182:185], v[44:47]
	v_mfma_f32_16x16x32_bf16 v[40:43], v[150:153], v[182:185], v[40:43]
	v_mfma_f32_16x16x32_bf16 v[28:31], v[138:141], v[200:203], v[28:31]
	v_mfma_f32_16x16x32_bf16 v[24:27], v[150:153], v[200:203], v[24:27]
	v_mfma_f32_16x16x32_bf16 v[12:15], v[138:141], v[208:211], v[12:15]
	v_mfma_f32_16x16x32_bf16 v[8:11], v[150:153], v[208:211], v[8:11]
	v_mfma_f32_16x16x32_bf16 v[60:63], v[146:149], v[178:181], v[60:63]
	v_mfma_f32_16x16x32_bf16 v[56:59], v[154:157], v[178:181], v[56:59]
	v_mfma_f32_16x16x32_bf16 v[44:47], v[146:149], v[186:189], v[44:47]
	v_mfma_f32_16x16x32_bf16 v[40:43], v[154:157], v[186:189], v[40:43]
	v_mfma_f32_16x16x32_bf16 v[28:31], v[146:149], v[204:207], v[28:31]
	v_mfma_f32_16x16x32_bf16 v[24:27], v[154:157], v[204:207], v[24:27]
	v_mfma_f32_16x16x32_bf16 v[12:15], v[146:149], v[212:215], v[12:15]
	v_mfma_f32_16x16x32_bf16 v[8:11], v[154:157], v[212:215], v[8:11]
	s_setprio 0
	s_setprio 1
	v_mfma_f32_16x16x32_bf16 v[52:55], v[158:161], v[174:177], v[52:55]
	v_mfma_f32_16x16x32_bf16 v[48:51], v[166:169], v[174:177], v[48:51]
	v_mfma_f32_16x16x32_bf16 v[36:39], v[158:161], v[182:185], v[36:39]
	v_mfma_f32_16x16x32_bf16 v[32:35], v[166:169], v[182:185], v[32:35]
	v_mfma_f32_16x16x32_bf16 v[20:23], v[158:161], v[200:203], v[20:23]
	v_mfma_f32_16x16x32_bf16 v[16:19], v[166:169], v[200:203], v[16:19]
	v_mfma_f32_16x16x32_bf16 v[4:7], v[158:161], v[208:211], v[4:7]
	v_mfma_f32_16x16x32_bf16 v[0:3], v[166:169], v[208:211], v[0:3]
	v_mfma_f32_16x16x32_bf16 v[52:55], v[162:165], v[178:181], v[52:55]
	v_mfma_f32_16x16x32_bf16 v[48:51], v[170:173], v[178:181], v[48:51]
	v_mfma_f32_16x16x32_bf16 v[36:39], v[162:165], v[186:189], v[36:39]
	v_mfma_f32_16x16x32_bf16 v[32:35], v[170:173], v[186:189], v[32:35]
	v_mfma_f32_16x16x32_bf16 v[20:23], v[162:165], v[204:207], v[20:23]
	v_mfma_f32_16x16x32_bf16 v[16:19], v[170:173], v[204:207], v[16:19]
	v_mfma_f32_16x16x32_bf16 v[4:7], v[162:165], v[212:215], v[4:7]
	v_mfma_f32_16x16x32_bf16 v[0:3], v[170:173], v[212:215], v[0:3]
	s_setprio 0
	s_barrier
	s_add_i32 s59, s59, 2
	s_add_u32 s55, s55, 0x100
	s_addc_u32 s58, s58, 0
	s_add_u32 s46, s46, 0x100
	s_addc_u32 s47, s47, 0
	s_cmp_gt_u32 s59, 13
	s_cbranch_scc0 .LBB0_36
	s_and_b64 vcc, exec, s[12:13]
	s_cbranch_vccz .LBB0_39
	s_barrier

; #define PG8_STAGE(bufoff, gbase, voff) do { _Pragma("unroll") for (int _i = 0; _i < 2; ++_i) \
;         __builtin_amdgcn_global_load_lds((const unsigned*)((const char*)(gbase) + (voff)[_i]), (PG8_LAS unsigned*)(lds + (bufoff) + ldsw + _i * 8192), 16, 0, 0); } while (0)
; #define PG8_LDA(dst, b, h) do { _Pragma("unroll") for (int m = 0; m < 4; ++m) _Pragma("unroll") for (int k = 0; k < 2; ++k) dst[m][k] = *(const PG8_LAS bf16x8*)(lds + PG8_SA(b, h) + aoff + m * 2048 + k * 1024); } while (0)
; #define PG8_LDB(dst, b, h) do { _Pragma("unroll") for (int n = 0; n < 2; ++n) _Pragma("unroll") for (int k = 0; k < 2; ++k) dst[n][k] = *(const PG8_LAS bf16x8*)(lds + PG8_SB(b, h) + boff + n * 2048 + k * 1024); } while (0)
; #define PG8_MMA(ai, bj, At, Bt) do { __builtin_amdgcn_s_setprio(1); _Pragma("unroll") for (int m = 0; m < 4; ++m) _Pragma("unroll") for (int n = 0; n < 2; ++n) _Pragma("unroll") for (int k = 0; k < 2; ++k) \
;         acc[ai][bj][m][n] = __builtin_amdgcn_mfma_f32_16x16x32_bf16(Bt[n][k], At[m][k], acc[ai][bj][m][n], 0, 0, 0); __builtin_amdgcn_s_setprio(0); } while (0)
; #define PG8_WAIT_V(n) asm volatile("s_waitcnt vmcnt(" #n ")" ::: "memory")
; #define PG8_WAIT_L(n) asm volatile("s_waitcnt lgkmcnt(" #n ")" ::: "memory")
; #define PG8_BAR __builtin_amdgcn_s_barrier()
; #define PG8_SCHED __builtin_amdgcn_sched_barrier(0)
; template <class Epi, class Sched, bool ALIGN_EPI = false, bool SP2 = false>
; __device__ __forceinline__ void gemm_phase(PG8_LAS unsigned char* lds, const Gemm g, const Sched& S, const Epi& E, const int tid) {
;     ...
;             const bool last = (t == nt - 2);
;             const char* a1 = cA + (size_t)(t + 1) * kstep;
;             const char* a2 = last ? nA : cA + (size_t)(t + 2) * kstep; const char* b2 = last ? nB : cB + (size_t)(t + 2) * kstep;
;             const char* a3 = a2 + kstep; const char* b3 = b2 + kstep;
;             if (last && has_next) S.a_ready(nxt);
;             if constexpr (SP2) {
;             PG8_LDB(B0, 0, 0); PG8_LDB(B1, 0, 1); PG8_SCHED; PG8_LDA(At, 0, 0); PG8_STAGE(PG8_SA(1, 1), a1 + hstepA, voffA);
;             PG8_WAIT_V(8); PG8_WAIT_L(0); PG8_BAR; PG8_MMA(0, 0, At, B0); PG8_MMA(0, 1, At, B1); PG8_BAR; PG8_SCHED;
;             PG8_LDA(At, 0, 1); PG8_STAGE(PG8_SB(0, 0), b2, voffB); PG8_STAGE(PG8_SB(0, 1), b2 + hstepB, voffB); PG8_STAGE(PG8_SA(0, 0), a2, voffA);
.LBB0_70:
	s_add_u32 s24, s50, 0xfffc0080
	s_addc_u32 s25, s51, -1
	s_add_i32 s68, 0, 0x10000
	s_cmp_eq_u32 s74, 12
	s_cselect_b32 s55, s19, s25
	s_cselect_b32 s54, s63, s24
	s_cselect_b32 s53, s13, s2
	s_cselect_b32 s52, s65, s78
	s_add_i32 s69, 0, 0x14000
	v_add_u32_e32 v140, s68, v155
	v_add_u32_e32 v166, s69, v155
	ds_read_b128 v[128:131], v140
	ds_read_b128 v[132:135], v140 offset:1024
	ds_read_b128 v[136:139], v140 offset:2048
	ds_read_b128 v[140:143], v140 offset:3072
	ds_read_b128 v[150:153], v166
	ds_read_b128 v[158:161], v166 offset:1024
	ds_read_b128 v[162:165], v166 offset:2048
	ds_read_b128 v[166:169], v166 offset:3072
	v_lshl_add_u64 v[190:191], s[50:51], 0, v[148:149]
	s_add_i32 m0, s21, 0xc000
	ds_read_b128 v[170:173], v157
	ds_read_b128 v[174:177], v157 offset:1024
	ds_read_b128 v[178:181], v157 offset:2048
	ds_read_b128 v[182:185], v157 offset:3072
	ds_read_b128 v[186:189], v157 offset:4096
	ds_read_b128 v[200:203], v157 offset:5120
	ds_read_b128 v[204:207], v157 offset:6144
	ds_read_b128 v[208:211], v157 offset:7168
	global_load_lds_dwordx4 v[190:191], off
	v_lshl_add_u64 v[190:191], s[50:51], 0, v[146:147]
	s_add_i32 m0, s21, 0xe000
	s_nop 0
	global_load_lds_dwordx4 v[190:191], off
	s_waitcnt vmcnt(8)
	s_waitcnt lgkmcnt(0)
	s_barrier
	s_setprio 1
	v_mfma_f32_16x16x32_bf16 v[124:127], v[128:131], v[170:173], v[124:127]
	v_mfma_f32_16x16x32_bf16 v[120:123], v[136:139], v[170:173], v[120:123]
	v_mfma_f32_16x16x32_bf16 v[108:111], v[128:131], v[178:181], v[108:111]
	v_mfma_f32_16x16x32_bf16 v[104:107], v[136:139], v[178:181], v[104:107]
	v_mfma_f32_16x16x32_bf16 v[92:95], v[128:131], v[186:189], v[92:95]
	v_mfma_f32_16x16x32_bf16 v[88:91], v[136:139], v[186:189], v[88:91]
	v_mfma_f32_16x16x32_bf16 v[84:87], v[128:131], v[204:207], v[84:87]
	v_mfma_f32_16x16x32_bf16 v[80:83], v[136:139], v[204:207], v[80:83]
	v_mfma_f32_16x16x32_bf16 v[124:127], v[132:135], v[174:177], v[124:127]
	v_mfma_f32_16x16x32_bf16 v[120:123], v[140:143], v[174:177], v[120:123]
	v_mfma_f32_16x16x32_bf16 v[108:111], v[132:135], v[182:185], v[108:111]
	v_mfma_f32_16x16x32_bf16 v[104:107], v[140:143], v[182:185], v[104:107]
	v_mfma_f32_16x16x32_bf16 v[92:95], v[132:135], v[200:203], v[92:95]
	v_mfma_f32_16x16x32_bf16 v[88:91], v[140:143], v[200:203], v[88:91]
	v_mfma_f32_16x16x32_bf16 v[84:87], v[132:135], v[208:211], v[84:87]
	v_mfma_f32_16x16x32_bf16 v[80:83], v[140:143], v[208:211], v[80:83]
	s_setprio 0
	s_setprio 1
	v_mfma_f32_16x16x32_bf16 v[116:119], v[150:153], v[170:173], v[116:119]
	v_mfma_f32_16x16x32_bf16 v[112:115], v[162:165], v[170:173], v[112:115]
	v_mfma_f32_16x16x32_bf16 v[100:103], v[150:153], v[178:181], v[100:103]
	v_mfma_f32_16x16x32_bf16 v[96:99], v[162:165], v[178:181], v[96:99]
	v_mfma_f32_16x16x32_bf16 v[76:79], v[150:153], v[186:189], v[76:79]
	v_mfma_f32_16x16x32_bf16 v[72:75], v[162:165], v[186:189], v[72:75]
	v_mfma_f32_16x16x32_bf16 v[68:71], v[150:153], v[204:207], v[68:71]
	v_mfma_f32_16x16x32_bf16 v[64:67], v[162:165], v[204:207], v[64:67]
	v_mfma_f32_16x16x32_bf16 v[116:119], v[158:161], v[174:177], v[116:119]
	v_mfma_f32_16x16x32_bf16 v[112:115], v[166:169], v[174:177], v[112:115]
	v_mfma_f32_16x16x32_bf16 v[100:103], v[158:161], v[182:185], v[100:103]
	v_mfma_f32_16x16x32_bf16 v[96:99], v[166:169], v[182:185], v[96:99]
	v_mfma_f32_16x16x32_bf16 v[76:79], v[158:161], v[200:203], v[76:79]
	v_mfma_f32_16x16x32_bf16 v[72:75], v[166:169], v[200:203], v[72:75]
	v_mfma_f32_16x16x32_bf16 v[68:71], v[158:161], v[208:211], v[68:71]
	v_mfma_f32_16x16x32_bf16 v[64:67], v[166:169], v[208:211], v[64:67]
	s_setprio 0
	s_barrier
	s_add_i32 s24, s68, s20
	v_lshl_add_u64 v[190:191], s[52:53], 0, v[192:193]
	s_mov_b32 m0, s24
	ds_read_b128 v[170:173], v157 offset:16384
	ds_read_b128 v[174:177], v157 offset:17408
	ds_read_b128 v[178:181], v157 offset:18432
	ds_read_b128 v[182:185], v157 offset:19456
	ds_read_b128 v[186:189], v157 offset:20480
	ds_read_b128 v[200:203], v157 offset:21504
	ds_read_b128 v[204:207], v157 offset:22528
	ds_read_b128 v[208:211], v157 offset:23552
	global_load_lds_dwordx4 v[190:191], off
	s_add_i32 m0, s24, 0x2000
	s_add_u32 s24, s52, 0x40000
	v_lshl_add_u64 v[212:213], s[52:53], 0, v[144:145]
	s_addc_u32 s25, s53, 0
	s_add_i32 s68, s69, s20
	global_load_lds_dwordx4 v[212:213], off
	v_lshl_add_u64 v[214:215], s[24:25], 0, v[192:193]
	s_mov_b32 m0, s68
	v_lshl_add_u64 v[216:217], s[54:55], 0, v[144:145]
	global_load_lds_dwordx4 v[214:215], off
	v_lshl_add_u64 v[214:215], s[24:25], 0, v[144:145]
	s_add_i32 m0, s68, 0x2000
	s_nop 0
	global_load_lds_dwordx4 v[214:215], off
	v_lshl_add_u64 v[214:215], s[54:55], 0, v[192:193]
	s_mov_b32 m0, s21
	s_nop 0
	global_load_lds_dwordx4 v[214:215], off
	s_mov_b32 m0, s26
	s_nop 0
	global_load_lds_dwordx4 v[216:217], off
	s_waitcnt vmcnt(8)
	s_waitcnt lgkmcnt(0)
	s_barrier
; #define PG8_STAGE(bufoff, gbase, voff) do { _Pragma("unroll") for (int _i = 0; _i < 2; ++_i) \
;         __builtin_amdgcn_global_load_lds((const unsigned*)((const char*)(gbase) + (voff)[_i]), (PG8_LAS unsigned*)(lds + (bufoff) + ldsw + _i * 8192), 16, 0, 0); } while (0)
; #define PG8_LDA(dst, b, h) do { _Pragma("unroll") for (int m = 0; m < 4; ++m) _Pragma("unroll") for (int k = 0; k < 2; ++k) dst[m][k] = *(const PG8_LAS bf16x8*)(lds + PG8_SA(b, h) + aoff + m * 2048 + k * 1024); } while (0)
; #define PG8_LDB(dst, b, h) do { _Pragma("unroll") for (int n = 0; n < 2; ++n) _Pragma("unroll") for (int k = 0; k < 2; ++k) dst[n][k] = *(const PG8_LAS bf16x8*)(lds + PG8_SB(b, h) + boff + n * 2048 + k * 1024); } while (0)
; #define PG8_MMA(ai, bj, At, Bt) do { __builtin_amdgcn_s_setprio(1); _Pragma("unroll") for (int m = 0; m < 4; ++m) _Pragma("unroll") for (int n = 0; n < 2; ++n) _Pragma("unroll") for (int k = 0; k < 2; ++k) \
;         acc[ai][bj][m][n] = __builtin_amdgcn_mfma_f32_16x16x32_bf16(Bt[n][k], At[m][k], acc[ai][bj][m][n], 0, 0, 0); __builtin_amdgcn_s_setprio(0); } while (0)
; #define PG8_WAIT_V(n) asm volatile("s_waitcnt vmcnt(" #n ")" ::: "memory")
; #define PG8_WAIT_L(n) asm volatile("s_waitcnt lgkmcnt(" #n ")" ::: "memory")
; #define PG8_BAR __builtin_amdgcn_s_barrier()
; #define PG8_SCHED __builtin_amdgcn_sched_barrier(0)
; template <class Epi, class Sched, bool ALIGN_EPI = false, bool SP2 = false>
; __device__ __forceinline__ void gemm_phase(PG8_LAS unsigned char* lds, const Gemm g, const Sched& S, const Epi& E, const int tid) {
;     ...
;             PG8_WAIT_V(8); PG8_WAIT_L(0); PG8_BAR; PG8_MMA(1, 0, At, B0); PG8_MMA(1, 1, At, B1); PG8_BAR; PG8_SCHED;
;             PG8_LDB(B0, 1, 0); PG8_LDB(B1, 1, 1); PG8_SCHED; PG8_LDA(At, 1, 0); PG8_STAGE(PG8_SA(0, 1), a2 + hstepA, voffA);
;             PG8_WAIT_V(8); PG8_WAIT_L(0); PG8_BAR; PG8_MMA(0, 0, At, B0); PG8_MMA(0, 1, At, B1); PG8_BAR; PG8_SCHED;
	s_setprio 1
	v_mfma_f32_16x16x32_bf16 v[60:63], v[128:131], v[170:173], v[60:63]
	v_mfma_f32_16x16x32_bf16 v[56:59], v[136:139], v[170:173], v[56:59]
	v_mfma_f32_16x16x32_bf16 v[52:55], v[128:131], v[178:181], v[52:55]
	v_mfma_f32_16x16x32_bf16 v[40:43], v[136:139], v[178:181], v[40:43]
	v_mfma_f32_16x16x32_bf16 v[28:31], v[128:131], v[186:189], v[28:31]
	v_mfma_f32_16x16x32_bf16 v[24:27], v[136:139], v[186:189], v[24:27]
	v_mfma_f32_16x16x32_bf16 v[16:19], v[128:131], v[204:207], v[16:19]
	v_mfma_f32_16x16x32_bf16 v[8:11], v[136:139], v[204:207], v[8:11]
	v_mfma_f32_16x16x32_bf16 v[60:63], v[132:135], v[174:177], v[60:63]
	v_mfma_f32_16x16x32_bf16 v[56:59], v[140:143], v[174:177], v[56:59]
	v_mfma_f32_16x16x32_bf16 v[52:55], v[132:135], v[182:185], v[52:55]
	v_mfma_f32_16x16x32_bf16 v[40:43], v[140:143], v[182:185], v[40:43]
	v_mfma_f32_16x16x32_bf16 v[28:31], v[132:135], v[200:203], v[28:31]
	v_mfma_f32_16x16x32_bf16 v[24:27], v[140:143], v[200:203], v[24:27]
	v_mfma_f32_16x16x32_bf16 v[16:19], v[132:135], v[208:211], v[16:19]
	v_mfma_f32_16x16x32_bf16 v[8:11], v[140:143], v[208:211], v[8:11]
	s_setprio 0
	s_setprio 1
	v_mfma_f32_16x16x32_bf16 v[48:51], v[150:153], v[170:173], v[48:51]
	v_mfma_f32_16x16x32_bf16 v[44:47], v[162:165], v[170:173], v[44:47]
	v_mfma_f32_16x16x32_bf16 v[36:39], v[150:153], v[178:181], v[36:39]
	v_mfma_f32_16x16x32_bf16 v[32:35], v[162:165], v[178:181], v[32:35]
	v_mfma_f32_16x16x32_bf16 v[20:23], v[150:153], v[186:189], v[20:23]
	v_mfma_f32_16x16x32_bf16 v[12:15], v[162:165], v[186:189], v[12:15]
	v_mfma_f32_16x16x32_bf16 v[4:7], v[150:153], v[204:207], v[4:7]
	v_mfma_f32_16x16x32_bf16 v[0:3], v[162:165], v[204:207], v[0:3]
	v_mfma_f32_16x16x32_bf16 v[48:51], v[158:161], v[174:177], v[48:51]
	v_mfma_f32_16x16x32_bf16 v[44:47], v[166:169], v[174:177], v[44:47]
	v_mfma_f32_16x16x32_bf16 v[36:39], v[158:161], v[182:185], v[36:39]
	v_mfma_f32_16x16x32_bf16 v[32:35], v[166:169], v[182:185], v[32:35]
	v_mfma_f32_16x16x32_bf16 v[20:23], v[158:161], v[200:203], v[20:23]
	v_mfma_f32_16x16x32_bf16 v[12:15], v[166:169], v[200:203], v[12:15]
	v_mfma_f32_16x16x32_bf16 v[4:7], v[158:161], v[208:211], v[4:7]
	v_mfma_f32_16x16x32_bf16 v[0:3], v[166:169], v[208:211], v[0:3]
	s_setprio 0
	s_barrier
	s_add_i32 s68, 0, 0x18000
	s_add_i32 s69, 0, 0x1c000
	v_add_u32_e32 v140, s68, v155
	v_add_u32_e32 v166, s69, v155
	ds_read_b128 v[128:131], v140
	ds_read_b128 v[132:135], v140 offset:1024
	ds_read_b128 v[136:139], v140 offset:2048
	ds_read_b128 v[140:143], v140 offset:3072
	ds_read_b128 v[150:153], v166
	ds_read_b128 v[158:161], v166 offset:1024
	ds_read_b128 v[162:165], v166 offset:2048
	ds_read_b128 v[166:169], v166 offset:3072
	s_add_u32 s24, s54, 0x40000
	s_addc_u32 s25, s55, 0
	s_mov_b32 m0, s27
	v_lshl_add_u64 v[218:219], s[24:25], 0, v[192:193]
	ds_read_b128 v[170:173], v157 offset:32768
	ds_read_b128 v[174:177], v157 offset:33792
	ds_read_b128 v[178:181], v157 offset:34816
	ds_read_b128 v[182:185], v157 offset:35840
	ds_read_b128 v[186:189], v157 offset:36864
	ds_read_b128 v[200:203], v157 offset:37888
	ds_read_b128 v[204:207], v157 offset:38912
	ds_read_b128 v[208:211], v157 offset:39936
	global_load_lds_dwordx4 v[218:219], off
	v_lshl_add_u64 v[218:219], s[24:25], 0, v[144:145]
	s_mov_b32 m0, s28
	s_nop 0
	global_load_lds_dwordx4 v[218:219], off
	s_waitcnt vmcnt(8)
	s_waitcnt lgkmcnt(0)
	s_barrier
	s_setprio 1
	v_mfma_f32_16x16x32_bf16 v[124:127], v[128:131], v[170:173], v[124:127]
	v_mfma_f32_16x16x32_bf16 v[120:123], v[136:139], v[170:173], v[120:123]
	v_mfma_f32_16x16x32_bf16 v[108:111], v[128:131], v[178:181], v[108:111]
	v_mfma_f32_16x16x32_bf16 v[104:107], v[136:139], v[178:181], v[104:107]
	v_mfma_f32_16x16x32_bf16 v[92:95], v[128:131], v[186:189], v[92:95]
	v_mfma_f32_16x16x32_bf16 v[88:91], v[136:139], v[186:189], v[88:91]
	v_mfma_f32_16x16x32_bf16 v[84:87], v[128:131], v[204:207], v[84:87]
	v_mfma_f32_16x16x32_bf16 v[80:83], v[136:139], v[204:207], v[80:83]
	v_mfma_f32_16x16x32_bf16 v[124:127], v[132:135], v[174:177], v[124:127]
	v_mfma_f32_16x16x32_bf16 v[120:123], v[140:143], v[174:177], v[120:123]
	v_mfma_f32_16x16x32_bf16 v[108:111], v[132:135], v[182:185], v[108:111]
	v_mfma_f32_16x16x32_bf16 v[104:107], v[140:143], v[182:185], v[104:107]
	v_mfma_f32_16x16x32_bf16 v[92:95], v[132:135], v[200:203], v[92:95]
	v_mfma_f32_16x16x32_bf16 v[88:91], v[140:143], v[200:203], v[88:91]
	v_mfma_f32_16x16x32_bf16 v[84:87], v[132:135], v[208:211], v[84:87]
	v_mfma_f32_16x16x32_bf16 v[80:83], v[140:143], v[208:211], v[80:83]
	s_setprio 0
	s_setprio 1
	v_mfma_f32_16x16x32_bf16 v[116:119], v[150:153], v[170:173], v[116:119]
	v_mfma_f32_16x16x32_bf16 v[112:115], v[162:165], v[170:173], v[112:115]
	v_mfma_f32_16x16x32_bf16 v[100:103], v[150:153], v[178:181], v[100:103]
	v_mfma_f32_16x16x32_bf16 v[96:99], v[162:165], v[178:181], v[96:99]
	v_mfma_f32_16x16x32_bf16 v[76:79], v[150:153], v[186:189], v[76:79]
	v_mfma_f32_16x16x32_bf16 v[72:75], v[162:165], v[186:189], v[72:75]
	v_mfma_f32_16x16x32_bf16 v[68:71], v[150:153], v[204:207], v[68:71]
	v_mfma_f32_16x16x32_bf16 v[64:67], v[162:165], v[204:207], v[64:67]
	v_mfma_f32_16x16x32_bf16 v[116:119], v[158:161], v[174:177], v[116:119]
	v_mfma_f32_16x16x32_bf16 v[112:115], v[166:169], v[174:177], v[112:115]
	v_mfma_f32_16x16x32_bf16 v[100:103], v[158:161], v[182:185], v[100:103]
	v_mfma_f32_16x16x32_bf16 v[96:99], v[166:169], v[182:185], v[96:99]
	v_mfma_f32_16x16x32_bf16 v[76:79], v[158:161], v[200:203], v[76:79]
	v_mfma_f32_16x16x32_bf16 v[72:75], v[166:169], v[200:203], v[72:75]
	v_mfma_f32_16x16x32_bf16 v[68:71], v[158:161], v[208:211], v[68:71]
	v_mfma_f32_16x16x32_bf16 v[64:67], v[166:169], v[208:211], v[64:67]
	s_setprio 0
	s_barrier
; #define PG8_STAGE(bufoff, gbase, voff) do { _Pragma("unroll") for (int _i = 0; _i < 2; ++_i) \
;         __builtin_amdgcn_global_load_lds((const unsigned*)((const char*)(gbase) + (voff)[_i]), (PG8_LAS unsigned*)(lds + (bufoff) + ldsw + _i * 8192), 16, 0, 0); } while (0)
; #define PG8_LDA(dst, b, h) do { _Pragma("unroll") for (int m = 0; m < 4; ++m) _Pragma("unroll") for (int k = 0; k < 2; ++k) dst[m][k] = *(const PG8_LAS bf16x8*)(lds + PG8_SA(b, h) + aoff + m * 2048 + k * 1024); } while (0)
; #define PG8_MMA(ai, bj, At, Bt) do { __builtin_amdgcn_s_setprio(1); _Pragma("unroll") for (int m = 0; m < 4; ++m) _Pragma("unroll") for (int n = 0; n < 2; ++n) _Pragma("unroll") for (int k = 0; k < 2; ++k) \
;         acc[ai][bj][m][n] = __builtin_amdgcn_mfma_f32_16x16x32_bf16(Bt[n][k], At[m][k], acc[ai][bj][m][n], 0, 0, 0); __builtin_amdgcn_s_setprio(0); } while (0)
; #define PG8_WAIT_V(n) asm volatile("s_waitcnt vmcnt(" #n ")" ::: "memory")
; #define PG8_WAIT_L(n) asm volatile("s_waitcnt lgkmcnt(" #n ")" ::: "memory")
; #define PG8_BAR __builtin_amdgcn_s_barrier()
; #define PG8_SCHED __builtin_amdgcn_sched_barrier(0)
; template <class Epi, class Sched, bool ALIGN_EPI = false, bool SP2 = false>
; __device__ __forceinline__ void gemm_phase(PG8_LAS unsigned char* lds, const Gemm g, const Sched& S, const Epi& E, const int tid) {
;     ...
;             PG8_LDA(At, 1, 1); PG8_STAGE(PG8_SB(1, 0), b3, voffB); PG8_STAGE(PG8_SB(1, 1), b3 + hstepB, voffB); PG8_STAGE(PG8_SA(1, 0), a3, voffA);
;             PG8_WAIT_V(8); PG8_WAIT_L(0); PG8_BAR; PG8_MMA(1, 0, At, B0); PG8_MMA(1, 1, At, B1); PG8_BAR; PG8_SCHED;
;     ...
;         if constexpr (ALIGN_EPI) { if (wr == 0) PG8_BAR; }
	s_add_i32 s24, s68, s20
	v_lshl_add_u64 v[190:191], v[190:191], 0, s[60:61]
	s_mov_b32 m0, s24
	ds_read_b128 v[170:173], v157 offset:49152
	ds_read_b128 v[174:177], v157 offset:50176
	ds_read_b128 v[178:181], v157 offset:51200
	ds_read_b128 v[182:185], v157 offset:52224
	ds_read_b128 v[186:189], v157 offset:53248
	ds_read_b128 v[200:203], v157 offset:54272
	ds_read_b128 v[204:207], v157 offset:55296
	ds_read_b128 v[208:211], v157 offset:56320
	global_load_lds_dwordx4 v[190:191], off
	s_add_i32 m0, s24, 0x2000
	s_add_u32 s24, s52, 0x40080
	v_lshl_add_u64 v[190:191], v[212:213], 0, s[60:61]
	s_addc_u32 s25, s53, 0
	s_add_i32 s52, s69, s20
	global_load_lds_dwordx4 v[190:191], off
	v_lshl_add_u64 v[190:191], s[24:25], 0, v[192:193]
	s_mov_b32 m0, s52
	s_nop 0
	global_load_lds_dwordx4 v[190:191], off
	v_lshl_add_u64 v[190:191], s[24:25], 0, v[144:145]
	s_add_i32 m0, s52, 0x2000
	s_nop 0
	global_load_lds_dwordx4 v[190:191], off
	v_lshl_add_u64 v[190:191], v[214:215], 0, s[60:61]
	s_mov_b32 m0, s39
	s_nop 0
	global_load_lds_dwordx4 v[190:191], off
	v_lshl_add_u64 v[190:191], v[216:217], 0, s[60:61]
	s_mov_b32 m0, s40
	s_nop 0
	global_load_lds_dwordx4 v[190:191], off
	s_waitcnt vmcnt(8)
	s_waitcnt lgkmcnt(0)
	s_barrier
	s_setprio 1
	v_mfma_f32_16x16x32_bf16 v[60:63], v[128:131], v[170:173], v[60:63]
	v_mfma_f32_16x16x32_bf16 v[56:59], v[136:139], v[170:173], v[56:59]
	v_mfma_f32_16x16x32_bf16 v[52:55], v[128:131], v[178:181], v[52:55]
	v_mfma_f32_16x16x32_bf16 v[40:43], v[136:139], v[178:181], v[40:43]
	v_mfma_f32_16x16x32_bf16 v[28:31], v[128:131], v[186:189], v[28:31]
	v_mfma_f32_16x16x32_bf16 v[24:27], v[136:139], v[186:189], v[24:27]
	v_mfma_f32_16x16x32_bf16 v[16:19], v[128:131], v[204:207], v[16:19]
	v_mfma_f32_16x16x32_bf16 v[8:11], v[136:139], v[204:207], v[8:11]
	v_mfma_f32_16x16x32_bf16 v[60:63], v[132:135], v[174:177], v[60:63]
	v_mfma_f32_16x16x32_bf16 v[56:59], v[140:143], v[174:177], v[56:59]
	v_mfma_f32_16x16x32_bf16 v[52:55], v[132:135], v[182:185], v[52:55]
	v_mfma_f32_16x16x32_bf16 v[40:43], v[140:143], v[182:185], v[40:43]
	v_mfma_f32_16x16x32_bf16 v[28:31], v[132:135], v[200:203], v[28:31]
	v_mfma_f32_16x16x32_bf16 v[24:27], v[140:143], v[200:203], v[24:27]
	v_mfma_f32_16x16x32_bf16 v[16:19], v[132:135], v[208:211], v[16:19]
	v_mfma_f32_16x16x32_bf16 v[8:11], v[140:143], v[208:211], v[8:11]
	s_setprio 0
	s_setprio 1
	v_mfma_f32_16x16x32_bf16 v[48:51], v[150:153], v[170:173], v[48:51]
	v_mfma_f32_16x16x32_bf16 v[44:47], v[162:165], v[170:173], v[44:47]
	v_mfma_f32_16x16x32_bf16 v[36:39], v[150:153], v[178:181], v[36:39]
	v_mfma_f32_16x16x32_bf16 v[32:35], v[162:165], v[178:181], v[32:35]
	v_mfma_f32_16x16x32_bf16 v[20:23], v[150:153], v[186:189], v[20:23]
	v_mfma_f32_16x16x32_bf16 v[12:15], v[162:165], v[186:189], v[12:15]
	v_mfma_f32_16x16x32_bf16 v[4:7], v[150:153], v[204:207], v[4:7]
	v_mfma_f32_16x16x32_bf16 v[0:3], v[162:165], v[204:207], v[0:3]
	v_mfma_f32_16x16x32_bf16 v[48:51], v[158:161], v[174:177], v[48:51]
	v_mfma_f32_16x16x32_bf16 v[44:47], v[166:169], v[174:177], v[44:47]
	v_mfma_f32_16x16x32_bf16 v[36:39], v[158:161], v[182:185], v[36:39]
	v_mfma_f32_16x16x32_bf16 v[32:35], v[166:169], v[182:185], v[32:35]
	v_mfma_f32_16x16x32_bf16 v[20:23], v[158:161], v[200:203], v[20:23]
	v_mfma_f32_16x16x32_bf16 v[12:15], v[166:169], v[200:203], v[12:15]
	v_mfma_f32_16x16x32_bf16 v[4:7], v[158:161], v[208:211], v[4:7]
	v_mfma_f32_16x16x32_bf16 v[0:3], v[166:169], v[208:211], v[0:3]
	s_setprio 0
	s_barrier
	s_add_i32 s74, s74, 2
	s_add_u32 s78, s78, 0x100
	s_addc_u32 s2, s2, 0
	s_add_u32 s50, s50, 0x100
	s_addc_u32 s51, s51, 0
	s_cmp_gt_u32 s74, 13
	s_cbranch_scc0 .LBB0_70
	s_and_b64 vcc, exec, s[10:11]
	s_cbranch_vccz .LBB0_73
	s_barrier

; #define PG8_STAGE(bufoff, gbase, voff) do { _Pragma("unroll") for (int _i = 0; _i < 2; ++_i) \
;         __builtin_amdgcn_global_load_lds((const unsigned*)((const char*)(gbase) + (voff)[_i]), (PG8_LAS unsigned*)(lds + (bufoff) + ldsw + _i * 8192), 16, 0, 0); } while (0)
; #define PG8_LDA(dst, b, h) do { _Pragma("unroll") for (int m = 0; m < 4; ++m) _Pragma("unroll") for (int k = 0; k < 2; ++k) dst[m][k] = *(const PG8_LAS bf16x8*)(lds + PG8_SA(b, h) + aoff + m * 2048 + k * 1024); } while (0)
; #define PG8_LDB(dst, b, h) do { _Pragma("unroll") for (int n = 0; n < 2; ++n) _Pragma("unroll") for (int k = 0; k < 2; ++k) dst[n][k] = *(const PG8_LAS bf16x8*)(lds + PG8_SB(b, h) + boff + n * 2048 + k * 1024); } while (0)
; #define PG8_MMA(ai, bj, At, Bt) do { __builtin_amdgcn_s_setprio(1); _Pragma("unroll") for (int m = 0; m < 4; ++m) _Pragma("unroll") for (int n = 0; n < 2; ++n) _Pragma("unroll") for (int k = 0; k < 2; ++k) \
;         acc[ai][bj][m][n] = __builtin_amdgcn_mfma_f32_16x16x32_bf16(Bt[n][k], At[m][k], acc[ai][bj][m][n], 0, 0, 0); __builtin_amdgcn_s_setprio(0); } while (0)
; #define PG8_WAIT_V(n) asm volatile("s_waitcnt vmcnt(" #n ")" ::: "memory")
; #define PG8_WAIT_L(n) asm volatile("s_waitcnt lgkmcnt(" #n ")" ::: "memory")
; #define PG8_BAR __builtin_amdgcn_s_barrier()
; #define PG8_SCHED __builtin_amdgcn_sched_barrier(0)
; template <class Epi, class Sched, bool ALIGN_EPI = false, bool SP2 = false>
; __device__ __forceinline__ void gemm_phase(PG8_LAS unsigned char* lds, const Gemm g, const Sched& S, const Epi& E, const int tid) {
;     ...
;             const bool last = (t == nt - 2);
;             const char* a1 = cA + (size_t)(t + 1) * kstep;
;             const char* a2 = last ? nA : cA + (size_t)(t + 2) * kstep; const char* b2 = last ? nB : cB + (size_t)(t + 2) * kstep;
;             const char* a3 = a2 + kstep; const char* b3 = b2 + kstep;
;             if (last && has_next) S.a_ready(nxt);
;             if constexpr (SP2) {
;             PG8_LDB(B0, 0, 0); PG8_LDB(B1, 0, 1); PG8_SCHED; PG8_LDA(At, 0, 0); PG8_STAGE(PG8_SA(1, 1), a1 + hstepA, voffA);
;             PG8_WAIT_V(8); PG8_WAIT_L(0); PG8_BAR; PG8_MMA(0, 0, At, B0); PG8_MMA(0, 1, At, B1); PG8_BAR; PG8_SCHED;
;             PG8_LDA(At, 0, 1); PG8_STAGE(PG8_SB(0, 0), b2, voffB); PG8_STAGE(PG8_SB(0, 1), b2 + hstepB, voffB); PG8_STAGE(PG8_SA(0, 0), a2, voffA);
.LBB0_90:
	s_add_u32 s25, s6, 0xfffe0080
	s_addc_u32 s68, s7, -1
	s_add_i32 s69, 0, 0x10000
	s_cmp_eq_u32 s24, 4
	s_cselect_b32 s89, s55, s68
	s_cselect_b32 s88, vcc_lo, s25
	s_cselect_b32 s87, s53, s74
	s_cselect_b32 s86, vcc_hi, s2
	s_add_i32 s25, 0, 0x14000
	v_add_u32_e32 v92, s69, v237
	v_add_u32_e32 v132, s25, v237
	ds_read_b128 v[64:67], v92
	ds_read_b128 v[76:79], v92 offset:1024
	ds_read_b128 v[80:83], v92 offset:2048
	ds_read_b128 v[92:95], v92 offset:3072
	ds_read_b128 v[104:107], v132
	ds_read_b128 v[116:119], v132 offset:1024
	ds_read_b128 v[128:131], v132 offset:2048
	ds_read_b128 v[132:135], v132 offset:3072
	v_lshl_add_u64 v[210:211], s[6:7], 0, v[208:209]
	s_add_i32 m0, s17, 0xc000
	ds_read_b128 v[160:163], v239
	ds_read_b128 v[164:167], v239 offset:1024
	ds_read_b128 v[168:171], v239 offset:2048
	ds_read_b128 v[172:175], v239 offset:3072
	ds_read_b128 v[176:179], v239 offset:4096
	ds_read_b128 v[180:183], v239 offset:5120
	ds_read_b128 v[184:187], v239 offset:6144
	ds_read_b128 v[188:191], v239 offset:7168
	global_load_lds_dwordx4 v[210:211], off
	v_lshl_add_u64 v[210:211], s[6:7], 0, v[206:207]
	s_add_i32 m0, s17, 0xe000
	s_nop 0
	global_load_lds_dwordx4 v[210:211], off
	s_waitcnt vmcnt(8)
	s_waitcnt lgkmcnt(0)
	s_barrier
	s_setprio 1
	v_mfma_f32_16x16x32_bf16 v[156:159], v[64:67], v[160:163], v[156:159]
	v_mfma_f32_16x16x32_bf16 v[152:155], v[80:83], v[160:163], v[152:155]
	v_mfma_f32_16x16x32_bf16 v[140:143], v[64:67], v[168:171], v[140:143]
	v_mfma_f32_16x16x32_bf16 v[136:139], v[80:83], v[168:171], v[136:139]
	v_mfma_f32_16x16x32_bf16 v[112:115], v[64:67], v[176:179], v[112:115]
	v_mfma_f32_16x16x32_bf16 v[108:111], v[80:83], v[176:179], v[108:111]
	v_mfma_f32_16x16x32_bf16 v[88:91], v[64:67], v[184:187], v[88:91]
	v_mfma_f32_16x16x32_bf16 v[84:87], v[80:83], v[184:187], v[84:87]
	v_mfma_f32_16x16x32_bf16 v[156:159], v[76:79], v[164:167], v[156:159]
	v_mfma_f32_16x16x32_bf16 v[152:155], v[92:95], v[164:167], v[152:155]
	v_mfma_f32_16x16x32_bf16 v[140:143], v[76:79], v[172:175], v[140:143]
	v_mfma_f32_16x16x32_bf16 v[136:139], v[92:95], v[172:175], v[136:139]
	v_mfma_f32_16x16x32_bf16 v[112:115], v[76:79], v[180:183], v[112:115]
	v_mfma_f32_16x16x32_bf16 v[108:111], v[92:95], v[180:183], v[108:111]
	v_mfma_f32_16x16x32_bf16 v[88:91], v[76:79], v[188:191], v[88:91]
	v_mfma_f32_16x16x32_bf16 v[84:87], v[92:95], v[188:191], v[84:87]
	s_setprio 0
	s_setprio 1
	v_mfma_f32_16x16x32_bf16 v[148:151], v[104:107], v[160:163], v[148:151]
	v_mfma_f32_16x16x32_bf16 v[144:147], v[128:131], v[160:163], v[144:147]
	v_mfma_f32_16x16x32_bf16 v[124:127], v[104:107], v[168:171], v[124:127]
	v_mfma_f32_16x16x32_bf16 v[120:123], v[128:131], v[168:171], v[120:123]
	v_mfma_f32_16x16x32_bf16 v[100:103], v[104:107], v[176:179], v[100:103]
	v_mfma_f32_16x16x32_bf16 v[96:99], v[128:131], v[176:179], v[96:99]
	v_mfma_f32_16x16x32_bf16 v[72:75], v[104:107], v[184:187], v[72:75]
	v_mfma_f32_16x16x32_bf16 v[68:71], v[128:131], v[184:187], v[68:71]
	v_mfma_f32_16x16x32_bf16 v[148:151], v[116:119], v[164:167], v[148:151]
	v_mfma_f32_16x16x32_bf16 v[144:147], v[132:135], v[164:167], v[144:147]
	v_mfma_f32_16x16x32_bf16 v[124:127], v[116:119], v[172:175], v[124:127]
	v_mfma_f32_16x16x32_bf16 v[120:123], v[132:135], v[172:175], v[120:123]
	v_mfma_f32_16x16x32_bf16 v[100:103], v[116:119], v[180:183], v[100:103]
	v_mfma_f32_16x16x32_bf16 v[96:99], v[132:135], v[180:183], v[96:99]
	v_mfma_f32_16x16x32_bf16 v[72:75], v[116:119], v[188:191], v[72:75]
	v_mfma_f32_16x16x32_bf16 v[68:71], v[132:135], v[188:191], v[68:71]
	s_setprio 0
	s_barrier
	s_add_i32 s68, s69, s16
	v_lshl_add_u64 v[210:211], s[86:87], 0, v[192:193]
	s_mov_b32 m0, s68
	ds_read_b128 v[160:163], v239 offset:16384
	ds_read_b128 v[164:167], v239 offset:17408
	ds_read_b128 v[168:171], v239 offset:18432
	ds_read_b128 v[172:175], v239 offset:19456
	ds_read_b128 v[176:179], v239 offset:20480
	ds_read_b128 v[180:183], v239 offset:21504
	ds_read_b128 v[184:187], v239 offset:22528
	ds_read_b128 v[188:191], v239 offset:23552
	global_load_lds_dwordx4 v[210:211], off
	s_add_i32 m0, s68, 0x2000
	s_add_u32 s68, s86, 0x20000
	v_lshl_add_u64 v[212:213], s[86:87], 0, v[204:205]
	s_addc_u32 s69, s87, 0
	s_add_i32 s25, s25, s16
	global_load_lds_dwordx4 v[212:213], off
	v_lshl_add_u64 v[214:215], s[68:69], 0, v[192:193]
	s_mov_b32 m0, s25
	v_lshl_add_u64 v[216:217], s[88:89], 0, v[202:203]
	global_load_lds_dwordx4 v[214:215], off
	v_lshl_add_u64 v[214:215], s[68:69], 0, v[204:205]
	s_add_i32 m0, s25, 0x2000
	s_nop 0
	global_load_lds_dwordx4 v[214:215], off
	v_lshl_add_u64 v[214:215], s[88:89], 0, v[200:201]
	s_mov_b32 m0, s17
	s_nop 0
	global_load_lds_dwordx4 v[214:215], off
	s_mov_b32 m0, s38
	s_nop 0
	global_load_lds_dwordx4 v[216:217], off
	s_waitcnt vmcnt(8)
	s_waitcnt lgkmcnt(0)
	s_barrier
; #define PG8_STAGE(bufoff, gbase, voff) do { _Pragma("unroll") for (int _i = 0; _i < 2; ++_i) \
;         __builtin_amdgcn_global_load_lds((const unsigned*)((const char*)(gbase) + (voff)[_i]), (PG8_LAS unsigned*)(lds + (bufoff) + ldsw + _i * 8192), 16, 0, 0); } while (0)
; #define PG8_LDA(dst, b, h) do { _Pragma("unroll") for (int m = 0; m < 4; ++m) _Pragma("unroll") for (int k = 0; k < 2; ++k) dst[m][k] = *(const PG8_LAS bf16x8*)(lds + PG8_SA(b, h) + aoff + m * 2048 + k * 1024); } while (0)
; #define PG8_LDB(dst, b, h) do { _Pragma("unroll") for (int n = 0; n < 2; ++n) _Pragma("unroll") for (int k = 0; k < 2; ++k) dst[n][k] = *(const PG8_LAS bf16x8*)(lds + PG8_SB(b, h) + boff + n * 2048 + k * 1024); } while (0)
; #define PG8_MMA(ai, bj, At, Bt) do { __builtin_amdgcn_s_setprio(1); _Pragma("unroll") for (int m = 0; m < 4; ++m) _Pragma("unroll") for (int n = 0; n < 2; ++n) _Pragma("unroll") for (int k = 0; k < 2; ++k) \
;         acc[ai][bj][m][n] = __builtin_amdgcn_mfma_f32_16x16x32_bf16(Bt[n][k], At[m][k], acc[ai][bj][m][n], 0, 0, 0); __builtin_amdgcn_s_setprio(0); } while (0)
; #define PG8_WAIT_V(n) asm volatile("s_waitcnt vmcnt(" #n ")" ::: "memory")
; #define PG8_WAIT_L(n) asm volatile("s_waitcnt lgkmcnt(" #n ")" ::: "memory")
; #define PG8_BAR __builtin_amdgcn_s_barrier()
; #define PG8_SCHED __builtin_amdgcn_sched_barrier(0)
; template <class Epi, class Sched, bool ALIGN_EPI = false, bool SP2 = false>
; __device__ __forceinline__ void gemm_phase(PG8_LAS unsigned char* lds, const Gemm g, const Sched& S, const Epi& E, const int tid) {
;     ...
;             PG8_WAIT_V(8); PG8_WAIT_L(0); PG8_BAR; PG8_MMA(1, 0, At, B0); PG8_MMA(1, 1, At, B1); PG8_BAR; PG8_SCHED;
;             PG8_LDB(B0, 1, 0); PG8_LDB(B1, 1, 1); PG8_SCHED; PG8_LDA(At, 1, 0); PG8_STAGE(PG8_SA(0, 1), a2 + hstepA, voffA);
;             PG8_WAIT_V(8); PG8_WAIT_L(0); PG8_BAR; PG8_MMA(0, 0, At, B0); PG8_MMA(0, 1, At, B1); PG8_BAR; PG8_SCHED;
	s_setprio 1
	v_mfma_f32_16x16x32_bf16 v[60:63], v[64:67], v[160:163], v[60:63]
	v_mfma_f32_16x16x32_bf16 v[56:59], v[80:83], v[160:163], v[56:59]
	v_mfma_f32_16x16x32_bf16 v[44:47], v[64:67], v[168:171], v[44:47]
	v_mfma_f32_16x16x32_bf16 v[40:43], v[80:83], v[168:171], v[40:43]
	v_mfma_f32_16x16x32_bf16 v[28:31], v[64:67], v[176:179], v[28:31]
	v_mfma_f32_16x16x32_bf16 v[24:27], v[80:83], v[176:179], v[24:27]
	v_mfma_f32_16x16x32_bf16 v[12:15], v[64:67], v[184:187], v[12:15]
	v_mfma_f32_16x16x32_bf16 v[8:11], v[80:83], v[184:187], v[8:11]
	v_mfma_f32_16x16x32_bf16 v[60:63], v[76:79], v[164:167], v[60:63]
	v_mfma_f32_16x16x32_bf16 v[56:59], v[92:95], v[164:167], v[56:59]
	v_mfma_f32_16x16x32_bf16 v[44:47], v[76:79], v[172:175], v[44:47]
	v_mfma_f32_16x16x32_bf16 v[40:43], v[92:95], v[172:175], v[40:43]
	v_mfma_f32_16x16x32_bf16 v[28:31], v[76:79], v[180:183], v[28:31]
	v_mfma_f32_16x16x32_bf16 v[24:27], v[92:95], v[180:183], v[24:27]
	v_mfma_f32_16x16x32_bf16 v[12:15], v[76:79], v[188:191], v[12:15]
	v_mfma_f32_16x16x32_bf16 v[8:11], v[92:95], v[188:191], v[8:11]
	s_setprio 0
	s_setprio 1
	v_mfma_f32_16x16x32_bf16 v[52:55], v[104:107], v[160:163], v[52:55]
	v_mfma_f32_16x16x32_bf16 v[48:51], v[128:131], v[160:163], v[48:51]
	v_mfma_f32_16x16x32_bf16 v[36:39], v[104:107], v[168:171], v[36:39]
	v_mfma_f32_16x16x32_bf16 v[32:35], v[128:131], v[168:171], v[32:35]
	v_mfma_f32_16x16x32_bf16 v[20:23], v[104:107], v[176:179], v[20:23]
	v_mfma_f32_16x16x32_bf16 v[16:19], v[128:131], v[176:179], v[16:19]
	v_mfma_f32_16x16x32_bf16 v[4:7], v[104:107], v[184:187], v[4:7]
	v_mfma_f32_16x16x32_bf16 v[0:3], v[128:131], v[184:187], v[0:3]
	v_mfma_f32_16x16x32_bf16 v[52:55], v[116:119], v[164:167], v[52:55]
	v_mfma_f32_16x16x32_bf16 v[48:51], v[132:135], v[164:167], v[48:51]
	v_mfma_f32_16x16x32_bf16 v[36:39], v[116:119], v[172:175], v[36:39]
	v_mfma_f32_16x16x32_bf16 v[32:35], v[132:135], v[172:175], v[32:35]
	v_mfma_f32_16x16x32_bf16 v[20:23], v[116:119], v[180:183], v[20:23]
	v_mfma_f32_16x16x32_bf16 v[16:19], v[132:135], v[180:183], v[16:19]
	v_mfma_f32_16x16x32_bf16 v[4:7], v[116:119], v[188:191], v[4:7]
	v_mfma_f32_16x16x32_bf16 v[0:3], v[132:135], v[188:191], v[0:3]
	s_setprio 0
	s_barrier
	s_add_i32 s25, 0, 0x18000
	s_add_i32 s56, 0, 0x1c000
	v_add_u32_e32 v92, s25, v237
	v_add_u32_e32 v132, s56, v237
	ds_read_b128 v[64:67], v92
	ds_read_b128 v[76:79], v92 offset:1024
	ds_read_b128 v[80:83], v92 offset:2048
	ds_read_b128 v[92:95], v92 offset:3072
	ds_read_b128 v[104:107], v132
	ds_read_b128 v[116:119], v132 offset:1024
	ds_read_b128 v[128:131], v132 offset:2048
	ds_read_b128 v[132:135], v132 offset:3072
	s_add_u32 s68, s88, 0x20000
	s_addc_u32 s69, s89, 0
	s_mov_b32 m0, s39
	v_lshl_add_u64 v[218:219], s[68:69], 0, v[200:201]
	ds_read_b128 v[160:163], v239 offset:32768
	ds_read_b128 v[164:167], v239 offset:33792
	ds_read_b128 v[168:171], v239 offset:34816
	ds_read_b128 v[172:175], v239 offset:35840
	ds_read_b128 v[176:179], v239 offset:36864
	ds_read_b128 v[180:183], v239 offset:37888
	ds_read_b128 v[184:187], v239 offset:38912
	ds_read_b128 v[188:191], v239 offset:39936
	global_load_lds_dwordx4 v[218:219], off
	v_lshl_add_u64 v[218:219], s[68:69], 0, v[202:203]
	s_mov_b32 m0, s28
	s_nop 0
	global_load_lds_dwordx4 v[218:219], off
	s_waitcnt vmcnt(8)
	s_waitcnt lgkmcnt(0)
	s_barrier
	s_setprio 1
	v_mfma_f32_16x16x32_bf16 v[156:159], v[64:67], v[160:163], v[156:159]
	v_mfma_f32_16x16x32_bf16 v[152:155], v[80:83], v[160:163], v[152:155]
	v_mfma_f32_16x16x32_bf16 v[140:143], v[64:67], v[168:171], v[140:143]
	v_mfma_f32_16x16x32_bf16 v[136:139], v[80:83], v[168:171], v[136:139]
	v_mfma_f32_16x16x32_bf16 v[112:115], v[64:67], v[176:179], v[112:115]
	v_mfma_f32_16x16x32_bf16 v[108:111], v[80:83], v[176:179], v[108:111]
	v_mfma_f32_16x16x32_bf16 v[88:91], v[64:67], v[184:187], v[88:91]
	v_mfma_f32_16x16x32_bf16 v[84:87], v[80:83], v[184:187], v[84:87]
	v_mfma_f32_16x16x32_bf16 v[156:159], v[76:79], v[164:167], v[156:159]
	v_mfma_f32_16x16x32_bf16 v[152:155], v[92:95], v[164:167], v[152:155]
	v_mfma_f32_16x16x32_bf16 v[140:143], v[76:79], v[172:175], v[140:143]
	v_mfma_f32_16x16x32_bf16 v[136:139], v[92:95], v[172:175], v[136:139]
	v_mfma_f32_16x16x32_bf16 v[112:115], v[76:79], v[180:183], v[112:115]
	v_mfma_f32_16x16x32_bf16 v[108:111], v[92:95], v[180:183], v[108:111]
	v_mfma_f32_16x16x32_bf16 v[88:91], v[76:79], v[188:191], v[88:91]
	v_mfma_f32_16x16x32_bf16 v[84:87], v[92:95], v[188:191], v[84:87]
	s_setprio 0
	s_setprio 1
	v_mfma_f32_16x16x32_bf16 v[148:151], v[104:107], v[160:163], v[148:151]
	v_mfma_f32_16x16x32_bf16 v[144:147], v[128:131], v[160:163], v[144:147]
	v_mfma_f32_16x16x32_bf16 v[124:127], v[104:107], v[168:171], v[124:127]
	v_mfma_f32_16x16x32_bf16 v[120:123], v[128:131], v[168:171], v[120:123]
	v_mfma_f32_16x16x32_bf16 v[100:103], v[104:107], v[176:179], v[100:103]
	v_mfma_f32_16x16x32_bf16 v[96:99], v[128:131], v[176:179], v[96:99]
	v_mfma_f32_16x16x32_bf16 v[72:75], v[104:107], v[184:187], v[72:75]
	v_mfma_f32_16x16x32_bf16 v[68:71], v[128:131], v[184:187], v[68:71]
	v_mfma_f32_16x16x32_bf16 v[148:151], v[116:119], v[164:167], v[148:151]
	v_mfma_f32_16x16x32_bf16 v[144:147], v[132:135], v[164:167], v[144:147]
	v_mfma_f32_16x16x32_bf16 v[124:127], v[116:119], v[172:175], v[124:127]
	v_mfma_f32_16x16x32_bf16 v[120:123], v[132:135], v[172:175], v[120:123]
	v_mfma_f32_16x16x32_bf16 v[100:103], v[116:119], v[180:183], v[100:103]
	v_mfma_f32_16x16x32_bf16 v[96:99], v[132:135], v[180:183], v[96:99]
	v_mfma_f32_16x16x32_bf16 v[72:75], v[116:119], v[188:191], v[72:75]
	v_mfma_f32_16x16x32_bf16 v[68:71], v[132:135], v[188:191], v[68:71]
	s_setprio 0
	s_barrier
; #define PG8_STAGE(bufoff, gbase, voff) do { _Pragma("unroll") for (int _i = 0; _i < 2; ++_i) \
;         __builtin_amdgcn_global_load_lds((const unsigned*)((const char*)(gbase) + (voff)[_i]), (PG8_LAS unsigned*)(lds + (bufoff) + ldsw + _i * 8192), 16, 0, 0); } while (0)
; #define PG8_LDA(dst, b, h) do { _Pragma("unroll") for (int m = 0; m < 4; ++m) _Pragma("unroll") for (int k = 0; k < 2; ++k) dst[m][k] = *(const PG8_LAS bf16x8*)(lds + PG8_SA(b, h) + aoff + m * 2048 + k * 1024); } while (0)
; #define PG8_MMA(ai, bj, At, Bt) do { __builtin_amdgcn_s_setprio(1); _Pragma("unroll") for (int m = 0; m < 4; ++m) _Pragma("unroll") for (int n = 0; n < 2; ++n) _Pragma("unroll") for (int k = 0; k < 2; ++k) \
;         acc[ai][bj][m][n] = __builtin_amdgcn_mfma_f32_16x16x32_bf16(Bt[n][k], At[m][k], acc[ai][bj][m][n], 0, 0, 0); __builtin_amdgcn_s_setprio(0); } while (0)
; #define PG8_WAIT_V(n) asm volatile("s_waitcnt vmcnt(" #n ")" ::: "memory")
; #define PG8_WAIT_L(n) asm volatile("s_waitcnt lgkmcnt(" #n ")" ::: "memory")
; #define PG8_BAR __builtin_amdgcn_s_barrier()
; #define PG8_SCHED __builtin_amdgcn_sched_barrier(0)
; template <class Epi, class Sched, bool ALIGN_EPI = false, bool SP2 = false>
; __device__ __forceinline__ void gemm_phase(PG8_LAS unsigned char* lds, const Gemm g, const Sched& S, const Epi& E, const int tid) {
;     ...
;             PG8_LDA(At, 1, 1); PG8_STAGE(PG8_SB(1, 0), b3, voffB); PG8_STAGE(PG8_SB(1, 1), b3 + hstepB, voffB); PG8_STAGE(PG8_SA(1, 0), a3, voffA);
;             PG8_WAIT_V(8); PG8_WAIT_L(0); PG8_BAR; PG8_MMA(1, 0, At, B0); PG8_MMA(1, 1, At, B1); PG8_BAR; PG8_SCHED;
;     ...
;         if constexpr (ALIGN_EPI) { if (wr == 0) PG8_BAR; }
	s_add_i32 s25, s25, s16
	v_lshl_add_u64 v[210:211], v[210:211], 0, s[60:61]
	s_mov_b32 m0, s25
	ds_read_b128 v[160:163], v239 offset:49152
	ds_read_b128 v[164:167], v239 offset:50176
	ds_read_b128 v[168:171], v239 offset:51200
	ds_read_b128 v[172:175], v239 offset:52224
	ds_read_b128 v[176:179], v239 offset:53248
	ds_read_b128 v[180:183], v239 offset:54272
	ds_read_b128 v[184:187], v239 offset:55296
	ds_read_b128 v[188:191], v239 offset:56320
	global_load_lds_dwordx4 v[210:211], off
	s_add_i32 m0, s25, 0x2000
	s_add_u32 s68, s86, 0x20080
	v_lshl_add_u64 v[210:211], v[212:213], 0, s[60:61]
	s_addc_u32 s69, s87, 0
	s_add_i32 s25, s56, s16
	global_load_lds_dwordx4 v[210:211], off
	v_lshl_add_u64 v[210:211], s[68:69], 0, v[192:193]
	s_mov_b32 m0, s25
	s_nop 0
	global_load_lds_dwordx4 v[210:211], off
	v_lshl_add_u64 v[210:211], s[68:69], 0, v[204:205]
	s_add_i32 m0, s25, 0x2000
	s_nop 0
	global_load_lds_dwordx4 v[210:211], off
	v_lshl_add_u64 v[210:211], v[214:215], 0, s[60:61]
	s_mov_b32 m0, s29
	s_nop 0
	global_load_lds_dwordx4 v[210:211], off
	v_lshl_add_u64 v[210:211], v[216:217], 0, s[60:61]
	s_mov_b32 m0, s14
	s_nop 0
	global_load_lds_dwordx4 v[210:211], off
	s_waitcnt vmcnt(8)
	s_waitcnt lgkmcnt(0)
	s_barrier
	s_setprio 1
	v_mfma_f32_16x16x32_bf16 v[60:63], v[64:67], v[160:163], v[60:63]
	v_mfma_f32_16x16x32_bf16 v[56:59], v[80:83], v[160:163], v[56:59]
	v_mfma_f32_16x16x32_bf16 v[44:47], v[64:67], v[168:171], v[44:47]
	v_mfma_f32_16x16x32_bf16 v[40:43], v[80:83], v[168:171], v[40:43]
	v_mfma_f32_16x16x32_bf16 v[28:31], v[64:67], v[176:179], v[28:31]
	v_mfma_f32_16x16x32_bf16 v[24:27], v[80:83], v[176:179], v[24:27]
	v_mfma_f32_16x16x32_bf16 v[12:15], v[64:67], v[184:187], v[12:15]
	v_mfma_f32_16x16x32_bf16 v[8:11], v[80:83], v[184:187], v[8:11]
	v_mfma_f32_16x16x32_bf16 v[60:63], v[76:79], v[164:167], v[60:63]
	v_mfma_f32_16x16x32_bf16 v[56:59], v[92:95], v[164:167], v[56:59]
	v_mfma_f32_16x16x32_bf16 v[44:47], v[76:79], v[172:175], v[44:47]
	v_mfma_f32_16x16x32_bf16 v[40:43], v[92:95], v[172:175], v[40:43]
	v_mfma_f32_16x16x32_bf16 v[28:31], v[76:79], v[180:183], v[28:31]
	v_mfma_f32_16x16x32_bf16 v[24:27], v[92:95], v[180:183], v[24:27]
	v_mfma_f32_16x16x32_bf16 v[12:15], v[76:79], v[188:191], v[12:15]
	v_mfma_f32_16x16x32_bf16 v[8:11], v[92:95], v[188:191], v[8:11]
	s_setprio 0
	s_setprio 1
	v_mfma_f32_16x16x32_bf16 v[52:55], v[104:107], v[160:163], v[52:55]
	v_mfma_f32_16x16x32_bf16 v[48:51], v[128:131], v[160:163], v[48:51]
	v_mfma_f32_16x16x32_bf16 v[36:39], v[104:107], v[168:171], v[36:39]
	v_mfma_f32_16x16x32_bf16 v[32:35], v[128:131], v[168:171], v[32:35]
	v_mfma_f32_16x16x32_bf16 v[20:23], v[104:107], v[176:179], v[20:23]
	v_mfma_f32_16x16x32_bf16 v[16:19], v[128:131], v[176:179], v[16:19]
	v_mfma_f32_16x16x32_bf16 v[4:7], v[104:107], v[184:187], v[4:7]
	v_mfma_f32_16x16x32_bf16 v[0:3], v[128:131], v[184:187], v[0:3]
	v_mfma_f32_16x16x32_bf16 v[52:55], v[116:119], v[164:167], v[52:55]
	v_mfma_f32_16x16x32_bf16 v[48:51], v[132:135], v[164:167], v[48:51]
	v_mfma_f32_16x16x32_bf16 v[36:39], v[116:119], v[172:175], v[36:39]
	v_mfma_f32_16x16x32_bf16 v[32:35], v[132:135], v[172:175], v[32:35]
	v_mfma_f32_16x16x32_bf16 v[20:23], v[116:119], v[180:183], v[20:23]
	v_mfma_f32_16x16x32_bf16 v[16:19], v[132:135], v[180:183], v[16:19]
	v_mfma_f32_16x16x32_bf16 v[4:7], v[116:119], v[188:191], v[4:7]
	v_mfma_f32_16x16x32_bf16 v[0:3], v[132:135], v[188:191], v[0:3]
	s_setprio 0
	s_barrier
	s_add_i32 s24, s24, 2
	s_add_u32 s2, s2, 0x100
	s_addc_u32 s74, s74, 0
	s_add_u32 s6, s6, 0x100
	s_addc_u32 s7, s7, 0
	s_cmp_gt_u32 s24, 5
	s_cbranch_scc0 .LBB0_90
	s_and_b64 vcc, exec, s[48:49]
	s_cbranch_vccz .LBB0_93
	s_barrier

; #define PG8_STAGE(bufoff, gbase, voff) do { _Pragma("unroll") for (int _i = 0; _i < 2; ++_i) \
;         __builtin_amdgcn_global_load_lds((const unsigned*)((const char*)(gbase) + (voff)[_i]), (PG8_LAS unsigned*)(lds + (bufoff) + ldsw + _i * 8192), 16, 0, 0); } while (0)
; #define PG8_LDA(dst, b, h) do { _Pragma("unroll") for (int m = 0; m < 4; ++m) _Pragma("unroll") for (int k = 0; k < 2; ++k) dst[m][k] = *(const PG8_LAS bf16x8*)(lds + PG8_SA(b, h) + aoff + m * 2048 + k * 1024); } while (0)
; #define PG8_LDB(dst, b, h) do { _Pragma("unroll") for (int n = 0; n < 2; ++n) _Pragma("unroll") for (int k = 0; k < 2; ++k) dst[n][k] = *(const PG8_LAS bf16x8*)(lds + PG8_SB(b, h) + boff + n * 2048 + k * 1024); } while (0)
; #define PG8_MMA(ai, bj, At, Bt) do { __builtin_amdgcn_s_setprio(1); _Pragma("unroll") for (int m = 0; m < 4; ++m) _Pragma("unroll") for (int n = 0; n < 2; ++n) _Pragma("unroll") for (int k = 0; k < 2; ++k) \
;         acc[ai][bj][m][n] = __builtin_amdgcn_mfma_f32_16x16x32_bf16(Bt[n][k], At[m][k], acc[ai][bj][m][n], 0, 0, 0); __builtin_amdgcn_s_setprio(0); } while (0)
; #define PG8_WAIT_V(n) asm volatile("s_waitcnt vmcnt(" #n ")" ::: "memory")
; #define PG8_WAIT_L(n) asm volatile("s_waitcnt lgkmcnt(" #n ")" ::: "memory")
; #define PG8_BAR __builtin_amdgcn_s_barrier()
; #define PG8_SCHED __builtin_amdgcn_sched_barrier(0)
; template <class Epi, class Sched, bool ALIGN_EPI = false, bool SP2 = false>
; __device__ __forceinline__ void gemm_phase(PG8_LAS unsigned char* lds, const Gemm g, const Sched& S, const Epi& E, const int tid) {
;     ...
;             const bool last = (t == nt - 2);
;             const char* a1 = cA + (size_t)(t + 1) * kstep;
;             const char* a2 = last ? nA : cA + (size_t)(t + 2) * kstep; const char* b2 = last ? nB : cB + (size_t)(t + 2) * kstep;
;             const char* a3 = a2 + kstep; const char* b3 = b2 + kstep;
;             if (last && has_next) S.a_ready(nxt);
;             if constexpr (SP2) {
;             PG8_LDB(B0, 0, 0); PG8_LDB(B1, 0, 1); PG8_SCHED; PG8_LDA(At, 0, 0); PG8_STAGE(PG8_SA(1, 1), a1 + hstepA, voffA);
;             PG8_WAIT_V(8); PG8_WAIT_L(0); PG8_BAR; PG8_MMA(0, 0, At, B0); PG8_MMA(0, 1, At, B1); PG8_BAR; PG8_SCHED;
;             PG8_LDA(At, 0, 1); PG8_STAGE(PG8_SB(0, 0), b2, voffB); PG8_STAGE(PG8_SB(0, 1), b2 + hstepB, voffB); PG8_STAGE(PG8_SA(0, 0), a2, voffA);
.LBB0_248:
	s_add_i32 vcc_lo, s52, 2
	s_add_u32 s50, s48, 0x100
	s_addc_u32 s51, s49, 0
	s_add_i32 s68, 0, 0x10000
	s_cmp_eq_u32 s87, s52
	s_cselect_b32 s53, s45, s51
	s_cselect_b32 s52, s44, s50
	v_add_u32_e32 v142, s68, v155
	s_cselect_b32 s43, s47, s25
	s_cselect_b32 s42, s46, s24
	s_add_i32 s69, 0, 0x14000
	ds_read_b128 v[138:141], v142
	ds_read_b128 v[158:161], v142 offset:1024
	ds_read_b128 v[162:165], v142 offset:2048
	ds_read_b128 v[166:169], v142 offset:3072
	v_add_u32_e32 v142, s69, v155
	ds_read_b128 v[170:173], v142
	ds_read_b128 v[174:177], v142 offset:1024
	ds_read_b128 v[178:181], v142 offset:2048
	ds_read_b128 v[182:185], v142 offset:3072
	v_lshl_add_u64 v[142:143], s[48:49], 0, v[134:135]
	s_add_i32 m0, s79, 0xc000
	ds_read_b128 v[186:189], v157
	ds_read_b128 v[200:203], v157 offset:1024
	ds_read_b128 v[204:207], v157 offset:2048
	ds_read_b128 v[208:211], v157 offset:3072
	ds_read_b128 v[212:215], v157 offset:4096
	ds_read_b128 v[216:219], v157 offset:5120
	ds_read_b128 v[220:223], v157 offset:6144
	ds_read_b128 v[234:237], v157 offset:7168
	global_load_lds_dwordx4 v[142:143], off
	v_lshl_add_u64 v[142:143], s[48:49], 0, v[132:133]
	s_add_i32 m0, s79, 0xe000
	s_nop 0
	global_load_lds_dwordx4 v[142:143], off
	s_waitcnt vmcnt(8)
	s_waitcnt lgkmcnt(0)
	s_barrier
	s_setprio 1
	v_mfma_f32_16x16x32_bf16 v[124:127], v[138:141], v[186:189], v[124:127]
	v_mfma_f32_16x16x32_bf16 v[120:123], v[162:165], v[186:189], v[120:123]
	v_mfma_f32_16x16x32_bf16 v[108:111], v[138:141], v[204:207], v[108:111]
	v_mfma_f32_16x16x32_bf16 v[104:107], v[162:165], v[204:207], v[104:107]
	v_mfma_f32_16x16x32_bf16 v[92:95], v[138:141], v[212:215], v[92:95]
	v_mfma_f32_16x16x32_bf16 v[88:91], v[162:165], v[212:215], v[88:91]
	v_mfma_f32_16x16x32_bf16 v[76:79], v[138:141], v[220:223], v[76:79]
	v_mfma_f32_16x16x32_bf16 v[72:75], v[162:165], v[220:223], v[72:75]
	v_mfma_f32_16x16x32_bf16 v[124:127], v[158:161], v[200:203], v[124:127]
	v_mfma_f32_16x16x32_bf16 v[120:123], v[166:169], v[200:203], v[120:123]
	v_mfma_f32_16x16x32_bf16 v[108:111], v[158:161], v[208:211], v[108:111]
	v_mfma_f32_16x16x32_bf16 v[104:107], v[166:169], v[208:211], v[104:107]
	v_mfma_f32_16x16x32_bf16 v[92:95], v[158:161], v[216:219], v[92:95]
	v_mfma_f32_16x16x32_bf16 v[88:91], v[166:169], v[216:219], v[88:91]
	v_mfma_f32_16x16x32_bf16 v[76:79], v[158:161], v[234:237], v[76:79]
	v_mfma_f32_16x16x32_bf16 v[72:75], v[166:169], v[234:237], v[72:75]
	s_setprio 0
	s_setprio 1
	v_mfma_f32_16x16x32_bf16 v[116:119], v[170:173], v[186:189], v[116:119]
	v_mfma_f32_16x16x32_bf16 v[112:115], v[178:181], v[186:189], v[112:115]
	v_mfma_f32_16x16x32_bf16 v[100:103], v[170:173], v[204:207], v[100:103]
	v_mfma_f32_16x16x32_bf16 v[96:99], v[178:181], v[204:207], v[96:99]
	v_mfma_f32_16x16x32_bf16 v[84:87], v[170:173], v[212:215], v[84:87]
	v_mfma_f32_16x16x32_bf16 v[80:83], v[178:181], v[212:215], v[80:83]
	v_mfma_f32_16x16x32_bf16 v[68:71], v[170:173], v[220:223], v[68:71]
	v_mfma_f32_16x16x32_bf16 v[64:67], v[178:181], v[220:223], v[64:67]
	v_mfma_f32_16x16x32_bf16 v[116:119], v[174:177], v[200:203], v[116:119]
	v_mfma_f32_16x16x32_bf16 v[112:115], v[182:185], v[200:203], v[112:115]
	v_mfma_f32_16x16x32_bf16 v[100:103], v[174:177], v[208:211], v[100:103]
	v_mfma_f32_16x16x32_bf16 v[96:99], v[182:185], v[208:211], v[96:99]
	v_mfma_f32_16x16x32_bf16 v[84:87], v[174:177], v[216:219], v[84:87]
	v_mfma_f32_16x16x32_bf16 v[80:83], v[182:185], v[216:219], v[80:83]
	v_mfma_f32_16x16x32_bf16 v[68:71], v[174:177], v[234:237], v[68:71]
	v_mfma_f32_16x16x32_bf16 v[64:67], v[182:185], v[234:237], v[64:67]
	s_setprio 0
	s_barrier
	s_add_i32 s48, s68, s65
	v_lshl_add_u64 v[142:143], s[42:43], 0, v[192:193]
	s_mov_b32 m0, s48
	ds_read_b128 v[186:189], v157 offset:16384
	ds_read_b128 v[200:203], v157 offset:17408
	ds_read_b128 v[204:207], v157 offset:18432
	ds_read_b128 v[208:211], v157 offset:19456
	ds_read_b128 v[212:215], v157 offset:20480
	ds_read_b128 v[216:219], v157 offset:21504
	ds_read_b128 v[220:223], v157 offset:22528
	ds_read_b128 v[234:237], v157 offset:23552
	global_load_lds_dwordx4 v[142:143], off
	s_add_i32 m0, s48, 0x2000
	v_lshl_add_u64 v[190:191], s[42:43], 0, v[136:137]
	s_add_u32 s42, s42, s55
	s_addc_u32 s43, s43, 0
	s_add_i32 s48, s69, s65
	global_load_lds_dwordx4 v[190:191], off
	v_lshl_add_u64 v[238:239], s[42:43], 0, v[192:193]
	s_mov_b32 m0, s48
	v_lshl_add_u64 v[240:241], s[42:43], 0, v[136:137]
	global_load_lds_dwordx4 v[238:239], off
	s_add_i32 m0, s48, 0x2000
	v_lshl_add_u64 v[242:243], s[52:53], 0, v[130:131]
	global_load_lds_dwordx4 v[240:241], off
	s_mov_b32 m0, s79
	v_lshl_add_u64 v[244:245], s[52:53], 0, v[128:129]
	global_load_lds_dwordx4 v[242:243], off
	s_mov_b32 m0, s80
	s_nop 0
	global_load_lds_dwordx4 v[244:245], off
	s_waitcnt vmcnt(8)
	s_waitcnt lgkmcnt(0)
	s_barrier
; #define PG8_STAGE(bufoff, gbase, voff) do { _Pragma("unroll") for (int _i = 0; _i < 2; ++_i) \
;         __builtin_amdgcn_global_load_lds((const unsigned*)((const char*)(gbase) + (voff)[_i]), (PG8_LAS unsigned*)(lds + (bufoff) + ldsw + _i * 8192), 16, 0, 0); } while (0)
; #define PG8_LDA(dst, b, h) do { _Pragma("unroll") for (int m = 0; m < 4; ++m) _Pragma("unroll") for (int k = 0; k < 2; ++k) dst[m][k] = *(const PG8_LAS bf16x8*)(lds + PG8_SA(b, h) + aoff + m * 2048 + k * 1024); } while (0)
; #define PG8_LDB(dst, b, h) do { _Pragma("unroll") for (int n = 0; n < 2; ++n) _Pragma("unroll") for (int k = 0; k < 2; ++k) dst[n][k] = *(const PG8_LAS bf16x8*)(lds + PG8_SB(b, h) + boff + n * 2048 + k * 1024); } while (0)
; #define PG8_MMA(ai, bj, At, Bt) do { __builtin_amdgcn_s_setprio(1); _Pragma("unroll") for (int m = 0; m < 4; ++m) _Pragma("unroll") for (int n = 0; n < 2; ++n) _Pragma("unroll") for (int k = 0; k < 2; ++k) \
;         acc[ai][bj][m][n] = __builtin_amdgcn_mfma_f32_16x16x32_bf16(Bt[n][k], At[m][k], acc[ai][bj][m][n], 0, 0, 0); __builtin_amdgcn_s_setprio(0); } while (0)
; #define PG8_WAIT_V(n) asm volatile("s_waitcnt vmcnt(" #n ")" ::: "memory")
; #define PG8_WAIT_L(n) asm volatile("s_waitcnt lgkmcnt(" #n ")" ::: "memory")
; #define PG8_BAR __builtin_amdgcn_s_barrier()
; #define PG8_SCHED __builtin_amdgcn_sched_barrier(0)
; template <class Epi, class Sched, bool ALIGN_EPI = false, bool SP2 = false>
; __device__ __forceinline__ void gemm_phase(PG8_LAS unsigned char* lds, const Gemm g, const Sched& S, const Epi& E, const int tid) {
;     ...
;             PG8_WAIT_V(8); PG8_WAIT_L(0); PG8_BAR; PG8_MMA(1, 0, At, B0); PG8_MMA(1, 1, At, B1); PG8_BAR; PG8_SCHED;
;             PG8_LDB(B0, 1, 0); PG8_LDB(B1, 1, 1); PG8_SCHED; PG8_LDA(At, 1, 0); PG8_STAGE(PG8_SA(0, 1), a2 + hstepA, voffA);
;             PG8_WAIT_V(8); PG8_WAIT_L(0); PG8_BAR; PG8_MMA(0, 0, At, B0); PG8_MMA(0, 1, At, B1); PG8_BAR; PG8_SCHED;
	s_setprio 1
	v_mfma_f32_16x16x32_bf16 v[60:63], v[138:141], v[186:189], v[60:63]
	v_mfma_f32_16x16x32_bf16 v[56:59], v[162:165], v[186:189], v[56:59]
	v_mfma_f32_16x16x32_bf16 v[44:47], v[138:141], v[204:207], v[44:47]
	v_mfma_f32_16x16x32_bf16 v[40:43], v[162:165], v[204:207], v[40:43]
	v_mfma_f32_16x16x32_bf16 v[28:31], v[138:141], v[212:215], v[28:31]
	v_mfma_f32_16x16x32_bf16 v[24:27], v[162:165], v[212:215], v[24:27]
	v_mfma_f32_16x16x32_bf16 v[12:15], v[138:141], v[220:223], v[12:15]
	v_mfma_f32_16x16x32_bf16 v[8:11], v[162:165], v[220:223], v[8:11]
	v_mfma_f32_16x16x32_bf16 v[60:63], v[158:161], v[200:203], v[60:63]
	v_mfma_f32_16x16x32_bf16 v[56:59], v[166:169], v[200:203], v[56:59]
	v_mfma_f32_16x16x32_bf16 v[44:47], v[158:161], v[208:211], v[44:47]
	v_mfma_f32_16x16x32_bf16 v[40:43], v[166:169], v[208:211], v[40:43]
	v_mfma_f32_16x16x32_bf16 v[28:31], v[158:161], v[216:219], v[28:31]
	v_mfma_f32_16x16x32_bf16 v[24:27], v[166:169], v[216:219], v[24:27]
	v_mfma_f32_16x16x32_bf16 v[12:15], v[158:161], v[234:237], v[12:15]
	v_mfma_f32_16x16x32_bf16 v[8:11], v[166:169], v[234:237], v[8:11]
	s_setprio 0
	s_setprio 1
	v_mfma_f32_16x16x32_bf16 v[52:55], v[170:173], v[186:189], v[52:55]
	v_mfma_f32_16x16x32_bf16 v[48:51], v[178:181], v[186:189], v[48:51]
	v_mfma_f32_16x16x32_bf16 v[36:39], v[170:173], v[204:207], v[36:39]
	v_mfma_f32_16x16x32_bf16 v[32:35], v[178:181], v[204:207], v[32:35]
	v_mfma_f32_16x16x32_bf16 v[20:23], v[170:173], v[212:215], v[20:23]
	v_mfma_f32_16x16x32_bf16 v[16:19], v[178:181], v[212:215], v[16:19]
	v_mfma_f32_16x16x32_bf16 v[4:7], v[170:173], v[220:223], v[4:7]
	v_mfma_f32_16x16x32_bf16 v[0:3], v[178:181], v[220:223], v[0:3]
	v_mfma_f32_16x16x32_bf16 v[52:55], v[174:177], v[200:203], v[52:55]
	v_mfma_f32_16x16x32_bf16 v[48:51], v[182:185], v[200:203], v[48:51]
	v_mfma_f32_16x16x32_bf16 v[36:39], v[174:177], v[208:211], v[36:39]
	v_mfma_f32_16x16x32_bf16 v[32:35], v[182:185], v[208:211], v[32:35]
	v_mfma_f32_16x16x32_bf16 v[20:23], v[174:177], v[216:219], v[20:23]
	v_mfma_f32_16x16x32_bf16 v[16:19], v[182:185], v[216:219], v[16:19]
	v_mfma_f32_16x16x32_bf16 v[4:7], v[174:177], v[234:237], v[4:7]
	v_mfma_f32_16x16x32_bf16 v[0:3], v[182:185], v[234:237], v[0:3]
	s_setprio 0
	s_barrier
	s_add_i32 s48, 0, 0x18000
	v_add_u32_e32 v144, s48, v155
	s_add_i32 s49, 0, 0x1c000
	ds_read_b128 v[138:141], v144
	ds_read_b128 v[158:161], v144 offset:1024
	ds_read_b128 v[162:165], v144 offset:2048
	ds_read_b128 v[166:169], v144 offset:3072
	v_add_u32_e32 v144, s49, v155
	ds_read_b128 v[170:173], v144
	ds_read_b128 v[174:177], v144 offset:1024
	ds_read_b128 v[178:181], v144 offset:2048
	ds_read_b128 v[182:185], v144 offset:3072
	s_add_u32 s42, s52, 0x30000
	s_addc_u32 s43, s53, 0
	s_mov_b32 m0, s81
	v_lshl_add_u64 v[246:247], s[42:43], 0, v[130:131]
	ds_read_b128 v[186:189], v157 offset:32768
	ds_read_b128 v[200:203], v157 offset:33792
	ds_read_b128 v[204:207], v157 offset:34816
	ds_read_b128 v[208:211], v157 offset:35840
	ds_read_b128 v[212:215], v157 offset:36864
	ds_read_b128 v[216:219], v157 offset:37888
	ds_read_b128 v[220:223], v157 offset:38912
	ds_read_b128 v[234:237], v157 offset:39936
	global_load_lds_dwordx4 v[246:247], off
	v_lshl_add_u64 v[246:247], s[42:43], 0, v[128:129]
	s_mov_b32 m0, s82
	s_nop 0
	global_load_lds_dwordx4 v[246:247], off
	s_waitcnt vmcnt(8)
	s_waitcnt lgkmcnt(0)
	s_barrier
	s_setprio 1
	v_mfma_f32_16x16x32_bf16 v[124:127], v[138:141], v[186:189], v[124:127]
	v_mfma_f32_16x16x32_bf16 v[120:123], v[162:165], v[186:189], v[120:123]
	v_mfma_f32_16x16x32_bf16 v[108:111], v[138:141], v[204:207], v[108:111]
	v_mfma_f32_16x16x32_bf16 v[104:107], v[162:165], v[204:207], v[104:107]
	v_mfma_f32_16x16x32_bf16 v[92:95], v[138:141], v[212:215], v[92:95]
	v_mfma_f32_16x16x32_bf16 v[88:91], v[162:165], v[212:215], v[88:91]
	v_mfma_f32_16x16x32_bf16 v[76:79], v[138:141], v[220:223], v[76:79]
	v_mfma_f32_16x16x32_bf16 v[72:75], v[162:165], v[220:223], v[72:75]
	v_mfma_f32_16x16x32_bf16 v[124:127], v[158:161], v[200:203], v[124:127]
	v_mfma_f32_16x16x32_bf16 v[120:123], v[166:169], v[200:203], v[120:123]
	v_mfma_f32_16x16x32_bf16 v[108:111], v[158:161], v[208:211], v[108:111]
	v_mfma_f32_16x16x32_bf16 v[104:107], v[166:169], v[208:211], v[104:107]
	v_mfma_f32_16x16x32_bf16 v[92:95], v[158:161], v[216:219], v[92:95]
	v_mfma_f32_16x16x32_bf16 v[88:91], v[166:169], v[216:219], v[88:91]
	v_mfma_f32_16x16x32_bf16 v[76:79], v[158:161], v[234:237], v[76:79]
	v_mfma_f32_16x16x32_bf16 v[72:75], v[166:169], v[234:237], v[72:75]
	s_setprio 0
	s_setprio 1
	v_mfma_f32_16x16x32_bf16 v[116:119], v[170:173], v[186:189], v[116:119]
	v_mfma_f32_16x16x32_bf16 v[112:115], v[178:181], v[186:189], v[112:115]
	v_mfma_f32_16x16x32_bf16 v[100:103], v[170:173], v[204:207], v[100:103]
	v_mfma_f32_16x16x32_bf16 v[96:99], v[178:181], v[204:207], v[96:99]
	v_mfma_f32_16x16x32_bf16 v[84:87], v[170:173], v[212:215], v[84:87]
	v_mfma_f32_16x16x32_bf16 v[80:83], v[178:181], v[212:215], v[80:83]
	v_mfma_f32_16x16x32_bf16 v[68:71], v[170:173], v[220:223], v[68:71]
	v_mfma_f32_16x16x32_bf16 v[64:67], v[178:181], v[220:223], v[64:67]
	v_mfma_f32_16x16x32_bf16 v[116:119], v[174:177], v[200:203], v[116:119]
	v_mfma_f32_16x16x32_bf16 v[112:115], v[182:185], v[200:203], v[112:115]
	v_mfma_f32_16x16x32_bf16 v[100:103], v[174:177], v[208:211], v[100:103]
	v_mfma_f32_16x16x32_bf16 v[96:99], v[182:185], v[208:211], v[96:99]
	v_mfma_f32_16x16x32_bf16 v[84:87], v[174:177], v[216:219], v[84:87]
	v_mfma_f32_16x16x32_bf16 v[80:83], v[182:185], v[216:219], v[80:83]
	v_mfma_f32_16x16x32_bf16 v[68:71], v[174:177], v[234:237], v[68:71]
	v_mfma_f32_16x16x32_bf16 v[64:67], v[182:185], v[234:237], v[64:67]
	s_setprio 0
	s_barrier
; #define PG8_STAGE(bufoff, gbase, voff) do { _Pragma("unroll") for (int _i = 0; _i < 2; ++_i) \
;         __builtin_amdgcn_global_load_lds((const unsigned*)((const char*)(gbase) + (voff)[_i]), (PG8_LAS unsigned*)(lds + (bufoff) + ldsw + _i * 8192), 16, 0, 0); } while (0)
; #define PG8_LDA(dst, b, h) do { _Pragma("unroll") for (int m = 0; m < 4; ++m) _Pragma("unroll") for (int k = 0; k < 2; ++k) dst[m][k] = *(const PG8_LAS bf16x8*)(lds + PG8_SA(b, h) + aoff + m * 2048 + k * 1024); } while (0)
; #define PG8_MMA(ai, bj, At, Bt) do { __builtin_amdgcn_s_setprio(1); _Pragma("unroll") for (int m = 0; m < 4; ++m) _Pragma("unroll") for (int n = 0; n < 2; ++n) _Pragma("unroll") for (int k = 0; k < 2; ++k) \
;         acc[ai][bj][m][n] = __builtin_amdgcn_mfma_f32_16x16x32_bf16(Bt[n][k], At[m][k], acc[ai][bj][m][n], 0, 0, 0); __builtin_amdgcn_s_setprio(0); } while (0)
; #define PG8_WAIT_V(n) asm volatile("s_waitcnt vmcnt(" #n ")" ::: "memory")
; #define PG8_WAIT_L(n) asm volatile("s_waitcnt lgkmcnt(" #n ")" ::: "memory")
; #define PG8_BAR __builtin_amdgcn_s_barrier()
; #define PG8_SCHED __builtin_amdgcn_sched_barrier(0)
; template <class Epi, class Sched, bool ALIGN_EPI = false, bool SP2 = false>
; __device__ __forceinline__ void gemm_phase(PG8_LAS unsigned char* lds, const Gemm g, const Sched& S, const Epi& E, const int tid) {
;     ...
;             PG8_LDA(At, 1, 1); PG8_STAGE(PG8_SB(1, 0), b3, voffB); PG8_STAGE(PG8_SB(1, 1), b3 + hstepB, voffB); PG8_STAGE(PG8_SA(1, 0), a3, voffA);
;             PG8_WAIT_V(8); PG8_WAIT_L(0); PG8_BAR; PG8_MMA(1, 0, At, B0); PG8_MMA(1, 1, At, B1); PG8_BAR; PG8_SCHED;
;     ...
;         if constexpr (ALIGN_EPI) { if (wr == 0) PG8_BAR; }
	s_add_i32 s42, s48, s65
	v_lshl_add_u64 v[142:143], v[142:143], 0, s[60:61]
	s_mov_b32 m0, s42
	ds_read_b128 v[186:189], v157 offset:49152
	ds_read_b128 v[200:203], v157 offset:50176
	ds_read_b128 v[204:207], v157 offset:51200
	ds_read_b128 v[208:211], v157 offset:52224
	ds_read_b128 v[212:215], v157 offset:53248
	ds_read_b128 v[216:219], v157 offset:54272
	ds_read_b128 v[220:223], v157 offset:55296
	ds_read_b128 v[234:237], v157 offset:56320
	global_load_lds_dwordx4 v[142:143], off
	v_lshl_add_u64 v[142:143], v[190:191], 0, s[60:61]
	s_add_i32 m0, s42, 0x2000
	s_add_i32 s42, s49, s65
	global_load_lds_dwordx4 v[142:143], off
	v_lshl_add_u64 v[142:143], v[238:239], 0, s[60:61]
	s_mov_b32 m0, s42
	s_nop 0
	global_load_lds_dwordx4 v[142:143], off
	v_lshl_add_u64 v[142:143], v[240:241], 0, s[60:61]
	s_add_i32 m0, s42, 0x2000
	s_nop 0
	global_load_lds_dwordx4 v[142:143], off
	v_lshl_add_u64 v[142:143], v[242:243], 0, s[60:61]
	s_mov_b32 m0, s85
	s_nop 0
	global_load_lds_dwordx4 v[142:143], off
	v_lshl_add_u64 v[142:143], v[244:245], 0, s[60:61]
	s_mov_b32 m0, s86
	s_nop 0
	global_load_lds_dwordx4 v[142:143], off
	s_waitcnt vmcnt(8)
	s_waitcnt lgkmcnt(0)
	s_barrier
	s_setprio 1
	v_mfma_f32_16x16x32_bf16 v[60:63], v[138:141], v[186:189], v[60:63]
	v_mfma_f32_16x16x32_bf16 v[56:59], v[162:165], v[186:189], v[56:59]
	v_mfma_f32_16x16x32_bf16 v[44:47], v[138:141], v[204:207], v[44:47]
	v_mfma_f32_16x16x32_bf16 v[40:43], v[162:165], v[204:207], v[40:43]
	v_mfma_f32_16x16x32_bf16 v[28:31], v[138:141], v[212:215], v[28:31]
	v_mfma_f32_16x16x32_bf16 v[24:27], v[162:165], v[212:215], v[24:27]
	v_mfma_f32_16x16x32_bf16 v[12:15], v[138:141], v[220:223], v[12:15]
	v_mfma_f32_16x16x32_bf16 v[8:11], v[162:165], v[220:223], v[8:11]
	v_mfma_f32_16x16x32_bf16 v[60:63], v[158:161], v[200:203], v[60:63]
	v_mfma_f32_16x16x32_bf16 v[56:59], v[166:169], v[200:203], v[56:59]
	v_mfma_f32_16x16x32_bf16 v[44:47], v[158:161], v[208:211], v[44:47]
	v_mfma_f32_16x16x32_bf16 v[40:43], v[166:169], v[208:211], v[40:43]
	v_mfma_f32_16x16x32_bf16 v[28:31], v[158:161], v[216:219], v[28:31]
	v_mfma_f32_16x16x32_bf16 v[24:27], v[166:169], v[216:219], v[24:27]
	v_mfma_f32_16x16x32_bf16 v[12:15], v[158:161], v[234:237], v[12:15]
	v_mfma_f32_16x16x32_bf16 v[8:11], v[166:169], v[234:237], v[8:11]
	s_setprio 0
	s_setprio 1
	v_mfma_f32_16x16x32_bf16 v[52:55], v[170:173], v[186:189], v[52:55]
	v_mfma_f32_16x16x32_bf16 v[48:51], v[178:181], v[186:189], v[48:51]
	v_mfma_f32_16x16x32_bf16 v[36:39], v[170:173], v[204:207], v[36:39]
	v_mfma_f32_16x16x32_bf16 v[32:35], v[178:181], v[204:207], v[32:35]
	v_mfma_f32_16x16x32_bf16 v[20:23], v[170:173], v[212:215], v[20:23]
	v_mfma_f32_16x16x32_bf16 v[16:19], v[178:181], v[212:215], v[16:19]
	v_mfma_f32_16x16x32_bf16 v[4:7], v[170:173], v[220:223], v[4:7]
	v_mfma_f32_16x16x32_bf16 v[0:3], v[178:181], v[220:223], v[0:3]
	v_mfma_f32_16x16x32_bf16 v[52:55], v[174:177], v[200:203], v[52:55]
	v_mfma_f32_16x16x32_bf16 v[48:51], v[182:185], v[200:203], v[48:51]
	v_mfma_f32_16x16x32_bf16 v[36:39], v[174:177], v[208:211], v[36:39]
	v_mfma_f32_16x16x32_bf16 v[32:35], v[182:185], v[208:211], v[32:35]
	v_mfma_f32_16x16x32_bf16 v[20:23], v[174:177], v[216:219], v[20:23]
	v_mfma_f32_16x16x32_bf16 v[16:19], v[182:185], v[216:219], v[16:19]
	v_mfma_f32_16x16x32_bf16 v[4:7], v[174:177], v[234:237], v[4:7]
	v_mfma_f32_16x16x32_bf16 v[0:3], v[182:185], v[234:237], v[0:3]
	s_setprio 0
	s_barrier
	s_add_u32 s24, s24, 0x100
	s_addc_u32 s25, s25, 0
	s_cmp_ge_u32 vcc_lo, s84
	s_mov_b64 s[48:49], s[50:51]
	s_mov_b32 s52, vcc_lo
	s_cbranch_scc0 .LBB0_248
	s_and_b64 vcc, exec, s[18:19]
	s_cbranch_vccz .LBB0_251
	s_barrier

; #define PG8_STAGE(bufoff, gbase, voff) do { _Pragma("unroll") for (int _i = 0; _i < 2; ++_i) \
;         __builtin_amdgcn_global_load_lds((const unsigned*)((const char*)(gbase) + (voff)[_i]), (PG8_LAS unsigned*)(lds + (bufoff) + ldsw + _i * 8192), 16, 0, 0); } while (0)
; #define PG8_LDA(dst, b, h) do { _Pragma("unroll") for (int m = 0; m < 4; ++m) _Pragma("unroll") for (int k = 0; k < 2; ++k) dst[m][k] = *(const PG8_LAS bf16x8*)(lds + PG8_SA(b, h) + aoff + m * 2048 + k * 1024); } while (0)
; #define PG8_LDB(dst, b, h) do { _Pragma("unroll") for (int n = 0; n < 2; ++n) _Pragma("unroll") for (int k = 0; k < 2; ++k) dst[n][k] = *(const PG8_LAS bf16x8*)(lds + PG8_SB(b, h) + boff + n * 2048 + k * 1024); } while (0)
; #define PG8_MMA(ai, bj, At, Bt) do { __builtin_amdgcn_s_setprio(1); _Pragma("unroll") for (int m = 0; m < 4; ++m) _Pragma("unroll") for (int n = 0; n < 2; ++n) _Pragma("unroll") for (int k = 0; k < 2; ++k) \
;         acc[ai][bj][m][n] = __builtin_amdgcn_mfma_f32_16x16x32_bf16(Bt[n][k], At[m][k], acc[ai][bj][m][n], 0, 0, 0); __builtin_amdgcn_s_setprio(0); } while (0)
; #define PG8_WAIT_V(n) asm volatile("s_waitcnt vmcnt(" #n ")" ::: "memory")
; #define PG8_WAIT_L(n) asm volatile("s_waitcnt lgkmcnt(" #n ")" ::: "memory")
; #define PG8_BAR __builtin_amdgcn_s_barrier()
; #define PG8_SCHED __builtin_amdgcn_sched_barrier(0)
; template <class Epi, class Sched, bool ALIGN_EPI = false, bool SP2 = false>
; __device__ __forceinline__ void gemm_phase(PG8_LAS unsigned char* lds, const Gemm g, const Sched& S, const Epi& E, const int tid) {
;     ...
;             const bool last = (t == nt - 2);
;             const char* a1 = cA + (size_t)(t + 1) * kstep;
;             const char* a2 = last ? nA : cA + (size_t)(t + 2) * kstep; const char* b2 = last ? nB : cB + (size_t)(t + 2) * kstep;
;             const char* a3 = a2 + kstep; const char* b3 = b2 + kstep;
;             if (last && has_next) S.a_ready(nxt);
;             if constexpr (SP2) {
;             PG8_LDB(B0, 0, 0); PG8_LDB(B1, 0, 1); PG8_SCHED; PG8_LDA(At, 0, 0); PG8_STAGE(PG8_SA(1, 1), a1 + hstepA, voffA);
;             PG8_WAIT_V(8); PG8_WAIT_L(0); PG8_BAR; PG8_MMA(0, 0, At, B0); PG8_MMA(0, 1, At, B1); PG8_BAR; PG8_SCHED;
;             PG8_LDA(At, 0, 1); PG8_STAGE(PG8_SB(0, 0), b2, voffB); PG8_STAGE(PG8_SB(0, 1), b2 + hstepB, voffB); PG8_STAGE(PG8_SA(0, 0), a2, voffA);
.LBB0_313:
	s_add_u32 s24, s50, 0xfffc0080
	s_addc_u32 s25, s51, -1
	s_add_i32 s68, 0, 0x10000
	s_cmp_eq_u32 s65, 12
	s_cselect_b32 s55, s40, s25
	s_cselect_b32 s54, s43, s24
	s_cselect_b32 s53, s39, s63
	s_cselect_b32 s52, s58, s59
	s_add_i32 s69, 0, 0x14000
	v_add_u32_e32 v154, s68, v139
	v_add_u32_e32 v170, s69, v139
	ds_read_b128 v[142:145], v154
	ds_read_b128 v[146:149], v154 offset:1024
	ds_read_b128 v[150:153], v154 offset:2048
	ds_read_b128 v[154:157], v154 offset:3072
	ds_read_b128 v[158:161], v170
	ds_read_b128 v[162:165], v170 offset:1024
	ds_read_b128 v[166:169], v170 offset:2048
	ds_read_b128 v[170:173], v170 offset:3072
	v_lshl_add_u64 v[190:191], s[50:51], 0, v[136:137]
	s_add_i32 m0, s21, 0xc000
	ds_read_b128 v[174:177], v141
	ds_read_b128 v[178:181], v141 offset:1024
	ds_read_b128 v[182:185], v141 offset:2048
	ds_read_b128 v[186:189], v141 offset:3072
	ds_read_b128 v[200:203], v141 offset:4096
	ds_read_b128 v[204:207], v141 offset:5120
	ds_read_b128 v[208:211], v141 offset:6144
	ds_read_b128 v[212:215], v141 offset:7168
	global_load_lds_dwordx4 v[190:191], off
	v_lshl_add_u64 v[190:191], s[50:51], 0, v[134:135]
	s_add_i32 m0, s21, 0xe000
	s_nop 0
	global_load_lds_dwordx4 v[190:191], off
	s_waitcnt vmcnt(8)
	s_waitcnt lgkmcnt(0)
	s_barrier
	s_setprio 1
	v_mfma_f32_16x16x32_bf16 v[124:127], v[142:145], v[174:177], v[124:127]
	v_mfma_f32_16x16x32_bf16 v[120:123], v[150:153], v[174:177], v[120:123]
	v_mfma_f32_16x16x32_bf16 v[116:119], v[142:145], v[182:185], v[116:119]
	v_mfma_f32_16x16x32_bf16 v[112:115], v[150:153], v[182:185], v[112:115]
	v_mfma_f32_16x16x32_bf16 v[100:103], v[142:145], v[200:203], v[100:103]
	v_mfma_f32_16x16x32_bf16 v[96:99], v[150:153], v[200:203], v[96:99]
	v_mfma_f32_16x16x32_bf16 v[84:87], v[142:145], v[208:211], v[84:87]
	v_mfma_f32_16x16x32_bf16 v[80:83], v[150:153], v[208:211], v[80:83]
	v_mfma_f32_16x16x32_bf16 v[124:127], v[146:149], v[178:181], v[124:127]
	v_mfma_f32_16x16x32_bf16 v[120:123], v[154:157], v[178:181], v[120:123]
	v_mfma_f32_16x16x32_bf16 v[116:119], v[146:149], v[186:189], v[116:119]
	v_mfma_f32_16x16x32_bf16 v[112:115], v[154:157], v[186:189], v[112:115]
	v_mfma_f32_16x16x32_bf16 v[100:103], v[146:149], v[204:207], v[100:103]
	v_mfma_f32_16x16x32_bf16 v[96:99], v[154:157], v[204:207], v[96:99]
	v_mfma_f32_16x16x32_bf16 v[84:87], v[146:149], v[212:215], v[84:87]
	v_mfma_f32_16x16x32_bf16 v[80:83], v[154:157], v[212:215], v[80:83]
	s_setprio 0
	s_setprio 1
	v_mfma_f32_16x16x32_bf16 v[108:111], v[158:161], v[174:177], v[108:111]
	v_mfma_f32_16x16x32_bf16 v[104:107], v[166:169], v[174:177], v[104:107]
	v_mfma_f32_16x16x32_bf16 v[92:95], v[158:161], v[182:185], v[92:95]
	v_mfma_f32_16x16x32_bf16 v[88:91], v[166:169], v[182:185], v[88:91]
	v_mfma_f32_16x16x32_bf16 v[76:79], v[158:161], v[200:203], v[76:79]
	v_mfma_f32_16x16x32_bf16 v[72:75], v[166:169], v[200:203], v[72:75]
	v_mfma_f32_16x16x32_bf16 v[68:71], v[158:161], v[208:211], v[68:71]
	v_mfma_f32_16x16x32_bf16 v[64:67], v[166:169], v[208:211], v[64:67]
	v_mfma_f32_16x16x32_bf16 v[108:111], v[162:165], v[178:181], v[108:111]
	v_mfma_f32_16x16x32_bf16 v[104:107], v[170:173], v[178:181], v[104:107]
	v_mfma_f32_16x16x32_bf16 v[92:95], v[162:165], v[186:189], v[92:95]
	v_mfma_f32_16x16x32_bf16 v[88:91], v[170:173], v[186:189], v[88:91]
	v_mfma_f32_16x16x32_bf16 v[76:79], v[162:165], v[204:207], v[76:79]
	v_mfma_f32_16x16x32_bf16 v[72:75], v[170:173], v[204:207], v[72:75]
	v_mfma_f32_16x16x32_bf16 v[68:71], v[162:165], v[212:215], v[68:71]
	v_mfma_f32_16x16x32_bf16 v[64:67], v[170:173], v[212:215], v[64:67]
	s_setprio 0
	s_barrier
	s_add_i32 s24, s68, s20
	v_lshl_add_u64 v[190:191], s[52:53], 0, v[192:193]
	s_mov_b32 m0, s24
	ds_read_b128 v[174:177], v141 offset:16384
	ds_read_b128 v[178:181], v141 offset:17408
	ds_read_b128 v[182:185], v141 offset:18432
	ds_read_b128 v[186:189], v141 offset:19456
	ds_read_b128 v[200:203], v141 offset:20480
	ds_read_b128 v[204:207], v141 offset:21504
	ds_read_b128 v[208:211], v141 offset:22528
	ds_read_b128 v[212:215], v141 offset:23552
	global_load_lds_dwordx4 v[190:191], off
	s_add_i32 m0, s24, 0x2000
	s_add_u32 s24, s52, 0x40000
	v_lshl_add_u64 v[216:217], s[52:53], 0, v[128:129]
	s_addc_u32 s25, s53, 0
	s_add_i32 s68, s69, s20
	global_load_lds_dwordx4 v[216:217], off
	v_lshl_add_u64 v[218:219], s[24:25], 0, v[192:193]
	s_mov_b32 m0, s68
	v_lshl_add_u64 v[220:221], s[54:55], 0, v[130:131]
	global_load_lds_dwordx4 v[218:219], off
	v_lshl_add_u64 v[218:219], s[24:25], 0, v[128:129]
	s_add_i32 m0, s68, 0x2000
	s_nop 0
	global_load_lds_dwordx4 v[218:219], off
	v_lshl_add_u64 v[218:219], s[54:55], 0, v[132:133]
	s_mov_b32 m0, s21
	s_nop 0
	global_load_lds_dwordx4 v[218:219], off
	s_mov_b32 m0, s26
	s_nop 0
	global_load_lds_dwordx4 v[220:221], off
	s_waitcnt vmcnt(8)
	s_waitcnt lgkmcnt(0)
	s_barrier
; #define PG8_STAGE(bufoff, gbase, voff) do { _Pragma("unroll") for (int _i = 0; _i < 2; ++_i) \
;         __builtin_amdgcn_global_load_lds((const unsigned*)((const char*)(gbase) + (voff)[_i]), (PG8_LAS unsigned*)(lds + (bufoff) + ldsw + _i * 8192), 16, 0, 0); } while (0)
; #define PG8_LDA(dst, b, h) do { _Pragma("unroll") for (int m = 0; m < 4; ++m) _Pragma("unroll") for (int k = 0; k < 2; ++k) dst[m][k] = *(const PG8_LAS bf16x8*)(lds + PG8_SA(b, h) + aoff + m * 2048 + k * 1024); } while (0)
; #define PG8_LDB(dst, b, h) do { _Pragma("unroll") for (int n = 0; n < 2; ++n) _Pragma("unroll") for (int k = 0; k < 2; ++k) dst[n][k] = *(const PG8_LAS bf16x8*)(lds + PG8_SB(b, h) + boff + n * 2048 + k * 1024); } while (0)
; #define PG8_MMA(ai, bj, At, Bt) do { __builtin_amdgcn_s_setprio(1); _Pragma("unroll") for (int m = 0; m < 4; ++m) _Pragma("unroll") for (int n = 0; n < 2; ++n) _Pragma("unroll") for (int k = 0; k < 2; ++k) \
;         acc[ai][bj][m][n] = __builtin_amdgcn_mfma_f32_16x16x32_bf16(Bt[n][k], At[m][k], acc[ai][bj][m][n], 0, 0, 0); __builtin_amdgcn_s_setprio(0); } while (0)
; #define PG8_WAIT_V(n) asm volatile("s_waitcnt vmcnt(" #n ")" ::: "memory")
; #define PG8_WAIT_L(n) asm volatile("s_waitcnt lgkmcnt(" #n ")" ::: "memory")
; #define PG8_BAR __builtin_amdgcn_s_barrier()
; #define PG8_SCHED __builtin_amdgcn_sched_barrier(0)
; template <class Epi, class Sched, bool ALIGN_EPI = false, bool SP2 = false>
; __device__ __forceinline__ void gemm_phase(PG8_LAS unsigned char* lds, const Gemm g, const Sched& S, const Epi& E, const int tid) {
;     ...
;             PG8_WAIT_V(8); PG8_WAIT_L(0); PG8_BAR; PG8_MMA(1, 0, At, B0); PG8_MMA(1, 1, At, B1); PG8_BAR; PG8_SCHED;
;             PG8_LDB(B0, 1, 0); PG8_LDB(B1, 1, 1); PG8_SCHED; PG8_LDA(At, 1, 0); PG8_STAGE(PG8_SA(0, 1), a2 + hstepA, voffA);
;             PG8_WAIT_V(8); PG8_WAIT_L(0); PG8_BAR; PG8_MMA(0, 0, At, B0); PG8_MMA(0, 1, At, B1); PG8_BAR; PG8_SCHED;
	s_setprio 1
	v_mfma_f32_16x16x32_bf16 v[60:63], v[142:145], v[174:177], v[60:63]
	v_mfma_f32_16x16x32_bf16 v[56:59], v[150:153], v[174:177], v[56:59]
	v_mfma_f32_16x16x32_bf16 v[52:55], v[142:145], v[182:185], v[52:55]
	v_mfma_f32_16x16x32_bf16 v[48:51], v[150:153], v[182:185], v[48:51]
	v_mfma_f32_16x16x32_bf16 v[36:39], v[142:145], v[200:203], v[36:39]
	v_mfma_f32_16x16x32_bf16 v[32:35], v[150:153], v[200:203], v[32:35]
	v_mfma_f32_16x16x32_bf16 v[20:23], v[142:145], v[208:211], v[20:23]
	v_mfma_f32_16x16x32_bf16 v[16:19], v[150:153], v[208:211], v[16:19]
	v_mfma_f32_16x16x32_bf16 v[60:63], v[146:149], v[178:181], v[60:63]
	v_mfma_f32_16x16x32_bf16 v[56:59], v[154:157], v[178:181], v[56:59]
	v_mfma_f32_16x16x32_bf16 v[52:55], v[146:149], v[186:189], v[52:55]
	v_mfma_f32_16x16x32_bf16 v[48:51], v[154:157], v[186:189], v[48:51]
	v_mfma_f32_16x16x32_bf16 v[36:39], v[146:149], v[204:207], v[36:39]
	v_mfma_f32_16x16x32_bf16 v[32:35], v[154:157], v[204:207], v[32:35]
	v_mfma_f32_16x16x32_bf16 v[20:23], v[146:149], v[212:215], v[20:23]
	v_mfma_f32_16x16x32_bf16 v[16:19], v[154:157], v[212:215], v[16:19]
	s_setprio 0
	s_setprio 1
	v_mfma_f32_16x16x32_bf16 v[44:47], v[158:161], v[174:177], v[44:47]
	v_mfma_f32_16x16x32_bf16 v[40:43], v[166:169], v[174:177], v[40:43]
	v_mfma_f32_16x16x32_bf16 v[28:31], v[158:161], v[182:185], v[28:31]
	v_mfma_f32_16x16x32_bf16 v[24:27], v[166:169], v[182:185], v[24:27]
	v_mfma_f32_16x16x32_bf16 v[12:15], v[158:161], v[200:203], v[12:15]
	v_mfma_f32_16x16x32_bf16 v[8:11], v[166:169], v[200:203], v[8:11]
	v_mfma_f32_16x16x32_bf16 v[4:7], v[158:161], v[208:211], v[4:7]
	v_mfma_f32_16x16x32_bf16 v[0:3], v[166:169], v[208:211], v[0:3]
	v_mfma_f32_16x16x32_bf16 v[44:47], v[162:165], v[178:181], v[44:47]
	v_mfma_f32_16x16x32_bf16 v[40:43], v[170:173], v[178:181], v[40:43]
	v_mfma_f32_16x16x32_bf16 v[28:31], v[162:165], v[186:189], v[28:31]
	v_mfma_f32_16x16x32_bf16 v[24:27], v[170:173], v[186:189], v[24:27]
	v_mfma_f32_16x16x32_bf16 v[12:15], v[162:165], v[204:207], v[12:15]
	v_mfma_f32_16x16x32_bf16 v[8:11], v[170:173], v[204:207], v[8:11]
	v_mfma_f32_16x16x32_bf16 v[4:7], v[162:165], v[212:215], v[4:7]
	v_mfma_f32_16x16x32_bf16 v[0:3], v[170:173], v[212:215], v[0:3]
	s_setprio 0
	s_barrier
	s_add_i32 s68, 0, 0x18000
	s_add_i32 s69, 0, 0x1c000
	v_add_u32_e32 v154, s68, v139
	v_add_u32_e32 v170, s69, v139
	ds_read_b128 v[142:145], v154
	ds_read_b128 v[146:149], v154 offset:1024
	ds_read_b128 v[150:153], v154 offset:2048
	ds_read_b128 v[154:157], v154 offset:3072
	ds_read_b128 v[158:161], v170
	ds_read_b128 v[162:165], v170 offset:1024
	ds_read_b128 v[166:169], v170 offset:2048
	ds_read_b128 v[170:173], v170 offset:3072
	s_add_u32 s24, s54, 0x40000
	s_addc_u32 s25, s55, 0
	s_mov_b32 m0, s27
	v_lshl_add_u64 v[222:223], s[24:25], 0, v[132:133]
	ds_read_b128 v[174:177], v141 offset:32768
	ds_read_b128 v[178:181], v141 offset:33792
	ds_read_b128 v[182:185], v141 offset:34816
	ds_read_b128 v[186:189], v141 offset:35840
	ds_read_b128 v[200:203], v141 offset:36864
	ds_read_b128 v[204:207], v141 offset:37888
	ds_read_b128 v[208:211], v141 offset:38912
	ds_read_b128 v[212:215], v141 offset:39936
	global_load_lds_dwordx4 v[222:223], off
	v_lshl_add_u64 v[222:223], s[24:25], 0, v[130:131]
	s_mov_b32 m0, s28
	s_nop 0
	global_load_lds_dwordx4 v[222:223], off
	s_waitcnt vmcnt(8)
	s_waitcnt lgkmcnt(0)
	s_barrier
	s_setprio 1
	v_mfma_f32_16x16x32_bf16 v[124:127], v[142:145], v[174:177], v[124:127]
	v_mfma_f32_16x16x32_bf16 v[120:123], v[150:153], v[174:177], v[120:123]
	v_mfma_f32_16x16x32_bf16 v[116:119], v[142:145], v[182:185], v[116:119]
	v_mfma_f32_16x16x32_bf16 v[112:115], v[150:153], v[182:185], v[112:115]
	v_mfma_f32_16x16x32_bf16 v[100:103], v[142:145], v[200:203], v[100:103]
	v_mfma_f32_16x16x32_bf16 v[96:99], v[150:153], v[200:203], v[96:99]
	v_mfma_f32_16x16x32_bf16 v[84:87], v[142:145], v[208:211], v[84:87]
	v_mfma_f32_16x16x32_bf16 v[80:83], v[150:153], v[208:211], v[80:83]
	v_mfma_f32_16x16x32_bf16 v[124:127], v[146:149], v[178:181], v[124:127]
	v_mfma_f32_16x16x32_bf16 v[120:123], v[154:157], v[178:181], v[120:123]
	v_mfma_f32_16x16x32_bf16 v[116:119], v[146:149], v[186:189], v[116:119]
	v_mfma_f32_16x16x32_bf16 v[112:115], v[154:157], v[186:189], v[112:115]
	v_mfma_f32_16x16x32_bf16 v[100:103], v[146:149], v[204:207], v[100:103]
	v_mfma_f32_16x16x32_bf16 v[96:99], v[154:157], v[204:207], v[96:99]
	v_mfma_f32_16x16x32_bf16 v[84:87], v[146:149], v[212:215], v[84:87]
	v_mfma_f32_16x16x32_bf16 v[80:83], v[154:157], v[212:215], v[80:83]
	s_setprio 0
	s_setprio 1
	v_mfma_f32_16x16x32_bf16 v[108:111], v[158:161], v[174:177], v[108:111]
	v_mfma_f32_16x16x32_bf16 v[104:107], v[166:169], v[174:177], v[104:107]
	v_mfma_f32_16x16x32_bf16 v[92:95], v[158:161], v[182:185], v[92:95]
	v_mfma_f32_16x16x32_bf16 v[88:91], v[166:169], v[182:185], v[88:91]
	v_mfma_f32_16x16x32_bf16 v[76:79], v[158:161], v[200:203], v[76:79]
	v_mfma_f32_16x16x32_bf16 v[72:75], v[166:169], v[200:203], v[72:75]
	v_mfma_f32_16x16x32_bf16 v[68:71], v[158:161], v[208:211], v[68:71]
	v_mfma_f32_16x16x32_bf16 v[64:67], v[166:169], v[208:211], v[64:67]
	v_mfma_f32_16x16x32_bf16 v[108:111], v[162:165], v[178:181], v[108:111]
	v_mfma_f32_16x16x32_bf16 v[104:107], v[170:173], v[178:181], v[104:107]
	v_mfma_f32_16x16x32_bf16 v[92:95], v[162:165], v[186:189], v[92:95]
	v_mfma_f32_16x16x32_bf16 v[88:91], v[170:173], v[186:189], v[88:91]
	v_mfma_f32_16x16x32_bf16 v[76:79], v[162:165], v[204:207], v[76:79]
	v_mfma_f32_16x16x32_bf16 v[72:75], v[170:173], v[204:207], v[72:75]
	v_mfma_f32_16x16x32_bf16 v[68:71], v[162:165], v[212:215], v[68:71]
	v_mfma_f32_16x16x32_bf16 v[64:67], v[170:173], v[212:215], v[64:67]
	s_setprio 0
	s_barrier
; #define PG8_STAGE(bufoff, gbase, voff) do { _Pragma("unroll") for (int _i = 0; _i < 2; ++_i) \
;         __builtin_amdgcn_global_load_lds((const unsigned*)((const char*)(gbase) + (voff)[_i]), (PG8_LAS unsigned*)(lds + (bufoff) + ldsw + _i * 8192), 16, 0, 0); } while (0)
; #define PG8_LDA(dst, b, h) do { _Pragma("unroll") for (int m = 0; m < 4; ++m) _Pragma("unroll") for (int k = 0; k < 2; ++k) dst[m][k] = *(const PG8_LAS bf16x8*)(lds + PG8_SA(b, h) + aoff + m * 2048 + k * 1024); } while (0)
; #define PG8_MMA(ai, bj, At, Bt) do { __builtin_amdgcn_s_setprio(1); _Pragma("unroll") for (int m = 0; m < 4; ++m) _Pragma("unroll") for (int n = 0; n < 2; ++n) _Pragma("unroll") for (int k = 0; k < 2; ++k) \
;         acc[ai][bj][m][n] = __builtin_amdgcn_mfma_f32_16x16x32_bf16(Bt[n][k], At[m][k], acc[ai][bj][m][n], 0, 0, 0); __builtin_amdgcn_s_setprio(0); } while (0)
; #define PG8_WAIT_V(n) asm volatile("s_waitcnt vmcnt(" #n ")" ::: "memory")
; #define PG8_WAIT_L(n) asm volatile("s_waitcnt lgkmcnt(" #n ")" ::: "memory")
; #define PG8_BAR __builtin_amdgcn_s_barrier()
; #define PG8_SCHED __builtin_amdgcn_sched_barrier(0)
; template <class Epi, class Sched, bool ALIGN_EPI = false, bool SP2 = false>
; __device__ __forceinline__ void gemm_phase(PG8_LAS unsigned char* lds, const Gemm g, const Sched& S, const Epi& E, const int tid) {
;     ...
;             PG8_LDA(At, 1, 1); PG8_STAGE(PG8_SB(1, 0), b3, voffB); PG8_STAGE(PG8_SB(1, 1), b3 + hstepB, voffB); PG8_STAGE(PG8_SA(1, 0), a3, voffA);
;             PG8_WAIT_V(8); PG8_WAIT_L(0); PG8_BAR; PG8_MMA(1, 0, At, B0); PG8_MMA(1, 1, At, B1); PG8_BAR; PG8_SCHED;
;     ...
;         if constexpr (ALIGN_EPI) { if (wr == 0) PG8_BAR; }
	s_add_i32 s24, s68, s20
	v_lshl_add_u64 v[190:191], v[190:191], 0, s[60:61]
	s_mov_b32 m0, s24
	ds_read_b128 v[174:177], v141 offset:49152
	ds_read_b128 v[178:181], v141 offset:50176
	ds_read_b128 v[182:185], v141 offset:51200
	ds_read_b128 v[186:189], v141 offset:52224
	ds_read_b128 v[200:203], v141 offset:53248
	ds_read_b128 v[204:207], v141 offset:54272
	ds_read_b128 v[208:211], v141 offset:55296
	ds_read_b128 v[212:215], v141 offset:56320
	global_load_lds_dwordx4 v[190:191], off
	s_add_i32 m0, s24, 0x2000
	s_add_u32 s24, s52, 0x40080
	v_lshl_add_u64 v[190:191], v[216:217], 0, s[60:61]
	s_addc_u32 s25, s53, 0
	s_add_i32 s52, s69, s20
	global_load_lds_dwordx4 v[190:191], off
	v_lshl_add_u64 v[190:191], s[24:25], 0, v[192:193]
	s_mov_b32 m0, s52
	s_nop 0
	global_load_lds_dwordx4 v[190:191], off
	v_lshl_add_u64 v[190:191], s[24:25], 0, v[128:129]
	s_add_i32 m0, s52, 0x2000
	s_nop 0
	global_load_lds_dwordx4 v[190:191], off
	v_lshl_add_u64 v[190:191], v[218:219], 0, s[60:61]
	s_mov_b32 m0, s29
	s_nop 0
	global_load_lds_dwordx4 v[190:191], off
	v_lshl_add_u64 v[190:191], v[220:221], 0, s[60:61]
	s_mov_b32 m0, s36
	s_nop 0
	global_load_lds_dwordx4 v[190:191], off
	s_waitcnt vmcnt(8)
	s_waitcnt lgkmcnt(0)
	s_barrier
	s_setprio 1
	v_mfma_f32_16x16x32_bf16 v[60:63], v[142:145], v[174:177], v[60:63]
	v_mfma_f32_16x16x32_bf16 v[56:59], v[150:153], v[174:177], v[56:59]
	v_mfma_f32_16x16x32_bf16 v[52:55], v[142:145], v[182:185], v[52:55]
	v_mfma_f32_16x16x32_bf16 v[48:51], v[150:153], v[182:185], v[48:51]
	v_mfma_f32_16x16x32_bf16 v[36:39], v[142:145], v[200:203], v[36:39]
	v_mfma_f32_16x16x32_bf16 v[32:35], v[150:153], v[200:203], v[32:35]
	v_mfma_f32_16x16x32_bf16 v[20:23], v[142:145], v[208:211], v[20:23]
	v_mfma_f32_16x16x32_bf16 v[16:19], v[150:153], v[208:211], v[16:19]
	v_mfma_f32_16x16x32_bf16 v[60:63], v[146:149], v[178:181], v[60:63]
	v_mfma_f32_16x16x32_bf16 v[56:59], v[154:157], v[178:181], v[56:59]
	v_mfma_f32_16x16x32_bf16 v[52:55], v[146:149], v[186:189], v[52:55]
	v_mfma_f32_16x16x32_bf16 v[48:51], v[154:157], v[186:189], v[48:51]
	v_mfma_f32_16x16x32_bf16 v[36:39], v[146:149], v[204:207], v[36:39]
	v_mfma_f32_16x16x32_bf16 v[32:35], v[154:157], v[204:207], v[32:35]
	v_mfma_f32_16x16x32_bf16 v[20:23], v[146:149], v[212:215], v[20:23]
	v_mfma_f32_16x16x32_bf16 v[16:19], v[154:157], v[212:215], v[16:19]
	s_setprio 0
	s_setprio 1
	v_mfma_f32_16x16x32_bf16 v[44:47], v[158:161], v[174:177], v[44:47]
	v_mfma_f32_16x16x32_bf16 v[40:43], v[166:169], v[174:177], v[40:43]
	v_mfma_f32_16x16x32_bf16 v[28:31], v[158:161], v[182:185], v[28:31]
	v_mfma_f32_16x16x32_bf16 v[24:27], v[166:169], v[182:185], v[24:27]
	v_mfma_f32_16x16x32_bf16 v[12:15], v[158:161], v[200:203], v[12:15]
	v_mfma_f32_16x16x32_bf16 v[8:11], v[166:169], v[200:203], v[8:11]
	v_mfma_f32_16x16x32_bf16 v[4:7], v[158:161], v[208:211], v[4:7]
	v_mfma_f32_16x16x32_bf16 v[0:3], v[166:169], v[208:211], v[0:3]
	v_mfma_f32_16x16x32_bf16 v[44:47], v[162:165], v[178:181], v[44:47]
	v_mfma_f32_16x16x32_bf16 v[40:43], v[170:173], v[178:181], v[40:43]
	v_mfma_f32_16x16x32_bf16 v[28:31], v[162:165], v[186:189], v[28:31]
	v_mfma_f32_16x16x32_bf16 v[24:27], v[170:173], v[186:189], v[24:27]
	v_mfma_f32_16x16x32_bf16 v[12:15], v[162:165], v[204:207], v[12:15]
	v_mfma_f32_16x16x32_bf16 v[8:11], v[170:173], v[204:207], v[8:11]
	v_mfma_f32_16x16x32_bf16 v[4:7], v[162:165], v[212:215], v[4:7]
	v_mfma_f32_16x16x32_bf16 v[0:3], v[170:173], v[212:215], v[0:3]
	s_setprio 0
	s_barrier
	s_add_i32 s65, s65, 2
	s_add_u32 s59, s59, 0x100
	s_addc_u32 s63, s63, 0
	s_add_u32 s50, s50, 0x100
	s_addc_u32 s51, s51, 0
	s_cmp_gt_u32 s65, 13
	s_cbranch_scc0 .LBB0_313
	s_and_b64 vcc, exec, s[14:15]
	s_cbranch_vccz .LBB0_316
	s_barrier

; #define PG8_STAGE(bufoff, gbase, voff) do { _Pragma("unroll") for (int _i = 0; _i < 2; ++_i) \
;         __builtin_amdgcn_global_load_lds((const unsigned*)((const char*)(gbase) + (voff)[_i]), (PG8_LAS unsigned*)(lds + (bufoff) + ldsw + _i * 8192), 16, 0, 0); } while (0)
; #define PG8_LDA(dst, b, h) do { _Pragma("unroll") for (int m = 0; m < 4; ++m) _Pragma("unroll") for (int k = 0; k < 2; ++k) dst[m][k] = *(const PG8_LAS bf16x8*)(lds + PG8_SA(b, h) + aoff + m * 2048 + k * 1024); } while (0)
; #define PG8_LDB(dst, b, h) do { _Pragma("unroll") for (int n = 0; n < 2; ++n) _Pragma("unroll") for (int k = 0; k < 2; ++k) dst[n][k] = *(const PG8_LAS bf16x8*)(lds + PG8_SB(b, h) + boff + n * 2048 + k * 1024); } while (0)
; #define PG8_MMA(ai, bj, At, Bt) do { __builtin_amdgcn_s_setprio(1); _Pragma("unroll") for (int m = 0; m < 4; ++m) _Pragma("unroll") for (int n = 0; n < 2; ++n) _Pragma("unroll") for (int k = 0; k < 2; ++k) \
;         acc[ai][bj][m][n] = __builtin_amdgcn_mfma_f32_16x16x32_bf16(Bt[n][k], At[m][k], acc[ai][bj][m][n], 0, 0, 0); __builtin_amdgcn_s_setprio(0); } while (0)
; #define PG8_WAIT_V(n) asm volatile("s_waitcnt vmcnt(" #n ")" ::: "memory")
; #define PG8_WAIT_L(n) asm volatile("s_waitcnt lgkmcnt(" #n ")" ::: "memory")
; #define PG8_BAR __builtin_amdgcn_s_barrier()
; #define PG8_SCHED __builtin_amdgcn_sched_barrier(0)
; template <class Epi, class Sched, bool ALIGN_EPI = false, bool SP2 = false>
; __device__ __forceinline__ void gemm_phase(PG8_LAS unsigned char* lds, const Gemm g, const Sched& S, const Epi& E, const int tid) {
;     ...
;             const bool last = (t == nt - 2);
;             const char* a1 = cA + (size_t)(t + 1) * kstep;
;             const char* a2 = last ? nA : cA + (size_t)(t + 2) * kstep; const char* b2 = last ? nB : cB + (size_t)(t + 2) * kstep;
;             const char* a3 = a2 + kstep; const char* b3 = b2 + kstep;
;             if (last && has_next) S.a_ready(nxt);
;             if constexpr (SP2) {
;             PG8_LDB(B0, 0, 0); PG8_LDB(B1, 0, 1); PG8_SCHED; PG8_LDA(At, 0, 0); PG8_STAGE(PG8_SA(1, 1), a1 + hstepA, voffA);
;             PG8_WAIT_V(8); PG8_WAIT_L(0); PG8_BAR; PG8_MMA(0, 0, At, B0); PG8_MMA(0, 1, At, B1); PG8_BAR; PG8_SCHED;
;             PG8_LDA(At, 0, 1); PG8_STAGE(PG8_SB(0, 0), b2, voffB); PG8_STAGE(PG8_SB(0, 1), b2 + hstepB, voffB); PG8_STAGE(PG8_SA(0, 0), a2, voffA);
.LBB0_347:
	s_add_u32 s48, s10, 0x100
	s_addc_u32 s49, s11, 0
	s_add_i32 s25, 0, 0x10000
	s_cmp_eq_u32 s24, 40
	s_cselect_b32 s53, s45, s49
	s_cselect_b32 s52, s44, s48
	s_cselect_b32 s51, s47, s21
	s_cselect_b32 s50, s46, s20
	s_add_i32 s26, 0, 0x14000
	v_add_u32_e32 v72, s25, v197
	v_add_u32_e32 v92, s26, v197
	ds_read_b128 v[60:63], v72
	ds_read_b128 v[64:67], v72 offset:1024
	ds_read_b128 v[68:71], v72 offset:2048
	ds_read_b128 v[72:75], v72 offset:3072
	ds_read_b128 v[76:79], v92
	ds_read_b128 v[80:83], v92 offset:1024
	ds_read_b128 v[88:91], v92 offset:2048
	ds_read_b128 v[92:95], v92 offset:3072
	v_lshl_add_u64 v[210:211], s[10:11], 0, v[180:181]
	s_add_i32 m0, s40, 0xc000
	ds_read_b128 v[160:163], v201
	ds_read_b128 v[164:167], v201 offset:1024
	ds_read_b128 v[168:171], v201 offset:2048
	ds_read_b128 v[172:175], v201 offset:3072
	ds_read_b128 v[182:185], v201 offset:4096
	ds_read_b128 v[186:189], v201 offset:5120
	ds_read_b128 v[202:205], v201 offset:6144
	ds_read_b128 v[206:209], v201 offset:7168
	global_load_lds_dwordx4 v[210:211], off
	v_lshl_add_u64 v[210:211], s[10:11], 0, v[178:179]
	s_add_i32 m0, s40, 0xe000
	s_nop 0
	global_load_lds_dwordx4 v[210:211], off
	s_waitcnt vmcnt(8)
	s_waitcnt lgkmcnt(0)
	s_barrier
	s_setprio 1
	v_mfma_f32_16x16x32_bf16 v[156:159], v[60:63], v[160:163], v[156:159]
	v_mfma_f32_16x16x32_bf16 v[152:155], v[68:71], v[160:163], v[152:155]
	v_mfma_f32_16x16x32_bf16 v[140:143], v[60:63], v[168:171], v[140:143]
	v_mfma_f32_16x16x32_bf16 v[136:139], v[68:71], v[168:171], v[136:139]
	v_mfma_f32_16x16x32_bf16 v[124:127], v[60:63], v[182:185], v[124:127]
	v_mfma_f32_16x16x32_bf16 v[120:123], v[68:71], v[182:185], v[120:123]
	v_mfma_f32_16x16x32_bf16 v[108:111], v[60:63], v[202:205], v[108:111]
	v_mfma_f32_16x16x32_bf16 v[104:107], v[68:71], v[202:205], v[104:107]
	v_mfma_f32_16x16x32_bf16 v[156:159], v[64:67], v[164:167], v[156:159]
	v_mfma_f32_16x16x32_bf16 v[152:155], v[72:75], v[164:167], v[152:155]
	v_mfma_f32_16x16x32_bf16 v[140:143], v[64:67], v[172:175], v[140:143]
	v_mfma_f32_16x16x32_bf16 v[136:139], v[72:75], v[172:175], v[136:139]
	v_mfma_f32_16x16x32_bf16 v[124:127], v[64:67], v[186:189], v[124:127]
	v_mfma_f32_16x16x32_bf16 v[120:123], v[72:75], v[186:189], v[120:123]
	v_mfma_f32_16x16x32_bf16 v[108:111], v[64:67], v[206:209], v[108:111]
	v_mfma_f32_16x16x32_bf16 v[104:107], v[72:75], v[206:209], v[104:107]
	s_setprio 0
	s_setprio 1
	v_mfma_f32_16x16x32_bf16 v[148:151], v[76:79], v[160:163], v[148:151]
	v_mfma_f32_16x16x32_bf16 v[144:147], v[88:91], v[160:163], v[144:147]
	v_mfma_f32_16x16x32_bf16 v[132:135], v[76:79], v[168:171], v[132:135]
	v_mfma_f32_16x16x32_bf16 v[128:131], v[88:91], v[168:171], v[128:131]
	v_mfma_f32_16x16x32_bf16 v[116:119], v[76:79], v[182:185], v[116:119]
	v_mfma_f32_16x16x32_bf16 v[112:115], v[88:91], v[182:185], v[112:115]
	v_mfma_f32_16x16x32_bf16 v[100:103], v[76:79], v[202:205], v[100:103]
	v_mfma_f32_16x16x32_bf16 v[96:99], v[88:91], v[202:205], v[96:99]
	v_mfma_f32_16x16x32_bf16 v[148:151], v[80:83], v[164:167], v[148:151]
	v_mfma_f32_16x16x32_bf16 v[144:147], v[92:95], v[164:167], v[144:147]
	v_mfma_f32_16x16x32_bf16 v[132:135], v[80:83], v[172:175], v[132:135]
	v_mfma_f32_16x16x32_bf16 v[128:131], v[92:95], v[172:175], v[128:131]
	v_mfma_f32_16x16x32_bf16 v[116:119], v[80:83], v[186:189], v[116:119]
	v_mfma_f32_16x16x32_bf16 v[112:115], v[92:95], v[186:189], v[112:115]
	v_mfma_f32_16x16x32_bf16 v[100:103], v[80:83], v[206:209], v[100:103]
	v_mfma_f32_16x16x32_bf16 v[96:99], v[92:95], v[206:209], v[96:99]
	s_setprio 0
	s_barrier
	s_add_i32 s10, s25, s23
	v_lshl_add_u64 v[210:211], s[50:51], 0, v[192:193]
	s_mov_b32 m0, s10
	ds_read_b128 v[160:163], v201 offset:16384
	ds_read_b128 v[164:167], v201 offset:17408
	ds_read_b128 v[168:171], v201 offset:18432
	ds_read_b128 v[172:175], v201 offset:19456
	ds_read_b128 v[182:185], v201 offset:20480
	ds_read_b128 v[186:189], v201 offset:21504
	ds_read_b128 v[202:205], v201 offset:22528
	ds_read_b128 v[206:209], v201 offset:23552
	global_load_lds_dwordx4 v[210:211], off
	s_add_i32 m0, s10, 0x2000
	s_add_u32 s10, s50, 0xb0000
	v_lshl_add_u64 v[212:213], s[50:51], 0, v[176:177]
	s_addc_u32 s11, s51, 0
	s_add_i32 s25, s26, s23
	global_load_lds_dwordx4 v[212:213], off
	v_lshl_add_u64 v[214:215], s[10:11], 0, v[192:193]
	s_mov_b32 m0, s25
	v_lshl_add_u64 v[216:217], s[52:53], 0, v[176:177]
	global_load_lds_dwordx4 v[214:215], off
	v_lshl_add_u64 v[214:215], s[10:11], 0, v[176:177]
	s_add_i32 m0, s25, 0x2000
	s_nop 0
	global_load_lds_dwordx4 v[214:215], off
	v_lshl_add_u64 v[214:215], s[52:53], 0, v[192:193]
	s_mov_b32 m0, s40
	s_nop 0
	global_load_lds_dwordx4 v[214:215], off
	s_mov_b32 m0, s54
	s_nop 0
	global_load_lds_dwordx4 v[216:217], off
	s_waitcnt vmcnt(8)
	s_waitcnt lgkmcnt(0)
	s_barrier
; #define PG8_STAGE(bufoff, gbase, voff) do { _Pragma("unroll") for (int _i = 0; _i < 2; ++_i) \
;         __builtin_amdgcn_global_load_lds((const unsigned*)((const char*)(gbase) + (voff)[_i]), (PG8_LAS unsigned*)(lds + (bufoff) + ldsw + _i * 8192), 16, 0, 0); } while (0)
; #define PG8_LDA(dst, b, h) do { _Pragma("unroll") for (int m = 0; m < 4; ++m) _Pragma("unroll") for (int k = 0; k < 2; ++k) dst[m][k] = *(const PG8_LAS bf16x8*)(lds + PG8_SA(b, h) + aoff + m * 2048 + k * 1024); } while (0)
; #define PG8_LDB(dst, b, h) do { _Pragma("unroll") for (int n = 0; n < 2; ++n) _Pragma("unroll") for (int k = 0; k < 2; ++k) dst[n][k] = *(const PG8_LAS bf16x8*)(lds + PG8_SB(b, h) + boff + n * 2048 + k * 1024); } while (0)
; #define PG8_MMA(ai, bj, At, Bt) do { __builtin_amdgcn_s_setprio(1); _Pragma("unroll") for (int m = 0; m < 4; ++m) _Pragma("unroll") for (int n = 0; n < 2; ++n) _Pragma("unroll") for (int k = 0; k < 2; ++k) \
;         acc[ai][bj][m][n] = __builtin_amdgcn_mfma_f32_16x16x32_bf16(Bt[n][k], At[m][k], acc[ai][bj][m][n], 0, 0, 0); __builtin_amdgcn_s_setprio(0); } while (0)
; #define PG8_WAIT_V(n) asm volatile("s_waitcnt vmcnt(" #n ")" ::: "memory")
; #define PG8_WAIT_L(n) asm volatile("s_waitcnt lgkmcnt(" #n ")" ::: "memory")
; #define PG8_BAR __builtin_amdgcn_s_barrier()
; #define PG8_SCHED __builtin_amdgcn_sched_barrier(0)
; template <class Epi, class Sched, bool ALIGN_EPI = false, bool SP2 = false>
; __device__ __forceinline__ void gemm_phase(PG8_LAS unsigned char* lds, const Gemm g, const Sched& S, const Epi& E, const int tid) {
;     ...
;             PG8_WAIT_V(8); PG8_WAIT_L(0); PG8_BAR; PG8_MMA(1, 0, At, B0); PG8_MMA(1, 1, At, B1); PG8_BAR; PG8_SCHED;
;             PG8_LDB(B0, 1, 0); PG8_LDB(B1, 1, 1); PG8_SCHED; PG8_LDA(At, 1, 0); PG8_STAGE(PG8_SA(0, 1), a2 + hstepA, voffA);
;             PG8_WAIT_V(8); PG8_WAIT_L(0); PG8_BAR; PG8_MMA(0, 0, At, B0); PG8_MMA(0, 1, At, B1); PG8_BAR; PG8_SCHED;
	s_setprio 1
	v_mfma_f32_16x16x32_bf16 v[84:87], v[60:63], v[160:163], v[84:87]
	v_mfma_f32_16x16x32_bf16 v[56:59], v[68:71], v[160:163], v[56:59]
	v_mfma_f32_16x16x32_bf16 v[44:47], v[60:63], v[168:171], v[44:47]
	v_mfma_f32_16x16x32_bf16 v[40:43], v[68:71], v[168:171], v[40:43]
	v_mfma_f32_16x16x32_bf16 v[28:31], v[60:63], v[182:185], v[28:31]
	v_mfma_f32_16x16x32_bf16 v[24:27], v[68:71], v[182:185], v[24:27]
	v_mfma_f32_16x16x32_bf16 v[12:15], v[60:63], v[202:205], v[12:15]
	v_mfma_f32_16x16x32_bf16 v[8:11], v[68:71], v[202:205], v[8:11]
	v_mfma_f32_16x16x32_bf16 v[84:87], v[64:67], v[164:167], v[84:87]
	v_mfma_f32_16x16x32_bf16 v[56:59], v[72:75], v[164:167], v[56:59]
	v_mfma_f32_16x16x32_bf16 v[44:47], v[64:67], v[172:175], v[44:47]
	v_mfma_f32_16x16x32_bf16 v[40:43], v[72:75], v[172:175], v[40:43]
	v_mfma_f32_16x16x32_bf16 v[28:31], v[64:67], v[186:189], v[28:31]
	v_mfma_f32_16x16x32_bf16 v[24:27], v[72:75], v[186:189], v[24:27]
	v_mfma_f32_16x16x32_bf16 v[12:15], v[64:67], v[206:209], v[12:15]
	v_mfma_f32_16x16x32_bf16 v[8:11], v[72:75], v[206:209], v[8:11]
	s_setprio 0
	s_setprio 1
	v_mfma_f32_16x16x32_bf16 v[52:55], v[76:79], v[160:163], v[52:55]
	v_mfma_f32_16x16x32_bf16 v[48:51], v[88:91], v[160:163], v[48:51]
	v_mfma_f32_16x16x32_bf16 v[36:39], v[76:79], v[168:171], v[36:39]
	v_mfma_f32_16x16x32_bf16 v[32:35], v[88:91], v[168:171], v[32:35]
	v_mfma_f32_16x16x32_bf16 v[20:23], v[76:79], v[182:185], v[20:23]
	v_mfma_f32_16x16x32_bf16 v[16:19], v[88:91], v[182:185], v[16:19]
	v_mfma_f32_16x16x32_bf16 v[4:7], v[76:79], v[202:205], v[4:7]
	v_mfma_f32_16x16x32_bf16 v[0:3], v[88:91], v[202:205], v[0:3]
	v_mfma_f32_16x16x32_bf16 v[52:55], v[80:83], v[164:167], v[52:55]
	v_mfma_f32_16x16x32_bf16 v[48:51], v[92:95], v[164:167], v[48:51]
	v_mfma_f32_16x16x32_bf16 v[36:39], v[80:83], v[172:175], v[36:39]
	v_mfma_f32_16x16x32_bf16 v[32:35], v[92:95], v[172:175], v[32:35]
	v_mfma_f32_16x16x32_bf16 v[20:23], v[80:83], v[186:189], v[20:23]
	v_mfma_f32_16x16x32_bf16 v[16:19], v[92:95], v[186:189], v[16:19]
	v_mfma_f32_16x16x32_bf16 v[4:7], v[80:83], v[206:209], v[4:7]
	v_mfma_f32_16x16x32_bf16 v[0:3], v[92:95], v[206:209], v[0:3]
	s_setprio 0
	s_barrier
	s_add_i32 s25, 0, 0x18000
	s_add_i32 s26, 0, 0x1c000
	v_add_u32_e32 v72, s25, v197
	v_add_u32_e32 v92, s26, v197
	ds_read_b128 v[60:63], v72
	ds_read_b128 v[64:67], v72 offset:1024
	ds_read_b128 v[68:71], v72 offset:2048
	ds_read_b128 v[72:75], v72 offset:3072
	ds_read_b128 v[76:79], v92
	ds_read_b128 v[80:83], v92 offset:1024
	ds_read_b128 v[88:91], v92 offset:2048
	ds_read_b128 v[92:95], v92 offset:3072
	s_add_u32 s10, s52, 0xb0000
	s_addc_u32 s11, s53, 0
	s_mov_b32 m0, s55
	v_lshl_add_u64 v[218:219], s[10:11], 0, v[192:193]
	ds_read_b128 v[160:163], v201 offset:32768
	ds_read_b128 v[164:167], v201 offset:33792
	ds_read_b128 v[168:171], v201 offset:34816
	ds_read_b128 v[172:175], v201 offset:35840
	ds_read_b128 v[182:185], v201 offset:36864
	ds_read_b128 v[186:189], v201 offset:37888
	ds_read_b128 v[202:205], v201 offset:38912
	ds_read_b128 v[206:209], v201 offset:39936
	global_load_lds_dwordx4 v[218:219], off
	v_lshl_add_u64 v[218:219], s[10:11], 0, v[176:177]
	s_mov_b32 m0, s58
	s_nop 0
	global_load_lds_dwordx4 v[218:219], off
	s_waitcnt vmcnt(8)
	s_waitcnt lgkmcnt(0)
	s_barrier
	s_setprio 1
	v_mfma_f32_16x16x32_bf16 v[156:159], v[60:63], v[160:163], v[156:159]
	v_mfma_f32_16x16x32_bf16 v[152:155], v[68:71], v[160:163], v[152:155]
	v_mfma_f32_16x16x32_bf16 v[140:143], v[60:63], v[168:171], v[140:143]
	v_mfma_f32_16x16x32_bf16 v[136:139], v[68:71], v[168:171], v[136:139]
	v_mfma_f32_16x16x32_bf16 v[124:127], v[60:63], v[182:185], v[124:127]
	v_mfma_f32_16x16x32_bf16 v[120:123], v[68:71], v[182:185], v[120:123]
	v_mfma_f32_16x16x32_bf16 v[108:111], v[60:63], v[202:205], v[108:111]
	v_mfma_f32_16x16x32_bf16 v[104:107], v[68:71], v[202:205], v[104:107]
	v_mfma_f32_16x16x32_bf16 v[156:159], v[64:67], v[164:167], v[156:159]
	v_mfma_f32_16x16x32_bf16 v[152:155], v[72:75], v[164:167], v[152:155]
	v_mfma_f32_16x16x32_bf16 v[140:143], v[64:67], v[172:175], v[140:143]
	v_mfma_f32_16x16x32_bf16 v[136:139], v[72:75], v[172:175], v[136:139]
	v_mfma_f32_16x16x32_bf16 v[124:127], v[64:67], v[186:189], v[124:127]
	v_mfma_f32_16x16x32_bf16 v[120:123], v[72:75], v[186:189], v[120:123]
	v_mfma_f32_16x16x32_bf16 v[108:111], v[64:67], v[206:209], v[108:111]
	v_mfma_f32_16x16x32_bf16 v[104:107], v[72:75], v[206:209], v[104:107]
	s_setprio 0
	s_setprio 1
	v_mfma_f32_16x16x32_bf16 v[148:151], v[76:79], v[160:163], v[148:151]
	v_mfma_f32_16x16x32_bf16 v[144:147], v[88:91], v[160:163], v[144:147]
	v_mfma_f32_16x16x32_bf16 v[132:135], v[76:79], v[168:171], v[132:135]
	v_mfma_f32_16x16x32_bf16 v[128:131], v[88:91], v[168:171], v[128:131]
	v_mfma_f32_16x16x32_bf16 v[116:119], v[76:79], v[182:185], v[116:119]
	v_mfma_f32_16x16x32_bf16 v[112:115], v[88:91], v[182:185], v[112:115]
	v_mfma_f32_16x16x32_bf16 v[100:103], v[76:79], v[202:205], v[100:103]
	v_mfma_f32_16x16x32_bf16 v[96:99], v[88:91], v[202:205], v[96:99]
	v_mfma_f32_16x16x32_bf16 v[148:151], v[80:83], v[164:167], v[148:151]
	v_mfma_f32_16x16x32_bf16 v[144:147], v[92:95], v[164:167], v[144:147]
	v_mfma_f32_16x16x32_bf16 v[132:135], v[80:83], v[172:175], v[132:135]
	v_mfma_f32_16x16x32_bf16 v[128:131], v[92:95], v[172:175], v[128:131]
	v_mfma_f32_16x16x32_bf16 v[116:119], v[80:83], v[186:189], v[116:119]
	v_mfma_f32_16x16x32_bf16 v[112:115], v[92:95], v[186:189], v[112:115]
	v_mfma_f32_16x16x32_bf16 v[100:103], v[80:83], v[206:209], v[100:103]
	v_mfma_f32_16x16x32_bf16 v[96:99], v[92:95], v[206:209], v[96:99]
	s_setprio 0
	s_barrier
; #define PG8_STAGE(bufoff, gbase, voff) do { _Pragma("unroll") for (int _i = 0; _i < 2; ++_i) \
;         __builtin_amdgcn_global_load_lds((const unsigned*)((const char*)(gbase) + (voff)[_i]), (PG8_LAS unsigned*)(lds + (bufoff) + ldsw + _i * 8192), 16, 0, 0); } while (0)
; #define PG8_LDA(dst, b, h) do { _Pragma("unroll") for (int m = 0; m < 4; ++m) _Pragma("unroll") for (int k = 0; k < 2; ++k) dst[m][k] = *(const PG8_LAS bf16x8*)(lds + PG8_SA(b, h) + aoff + m * 2048 + k * 1024); } while (0)
; #define PG8_MMA(ai, bj, At, Bt) do { __builtin_amdgcn_s_setprio(1); _Pragma("unroll") for (int m = 0; m < 4; ++m) _Pragma("unroll") for (int n = 0; n < 2; ++n) _Pragma("unroll") for (int k = 0; k < 2; ++k) \
;         acc[ai][bj][m][n] = __builtin_amdgcn_mfma_f32_16x16x32_bf16(Bt[n][k], At[m][k], acc[ai][bj][m][n], 0, 0, 0); __builtin_amdgcn_s_setprio(0); } while (0)
; #define PG8_WAIT_V(n) asm volatile("s_waitcnt vmcnt(" #n ")" ::: "memory")
; #define PG8_WAIT_L(n) asm volatile("s_waitcnt lgkmcnt(" #n ")" ::: "memory")
; #define PG8_BAR __builtin_amdgcn_s_barrier()
; #define PG8_SCHED __builtin_amdgcn_sched_barrier(0)
; template <class Epi, class Sched, bool ALIGN_EPI = false, bool SP2 = false>
; __device__ __forceinline__ void gemm_phase(PG8_LAS unsigned char* lds, const Gemm g, const Sched& S, const Epi& E, const int tid) {
;     ...
;             PG8_LDA(At, 1, 1); PG8_STAGE(PG8_SB(1, 0), b3, voffB); PG8_STAGE(PG8_SB(1, 1), b3 + hstepB, voffB); PG8_STAGE(PG8_SA(1, 0), a3, voffA);
;             PG8_WAIT_V(8); PG8_WAIT_L(0); PG8_BAR; PG8_MMA(1, 0, At, B0); PG8_MMA(1, 1, At, B1); PG8_BAR; PG8_SCHED;
;     ...
;         if constexpr (ALIGN_EPI) { if (wr == 0) PG8_BAR; }
	s_add_i32 s10, s25, s23
	v_lshl_add_u64 v[210:211], v[210:211], 0, s[60:61]
	s_mov_b32 m0, s10
	ds_read_b128 v[160:163], v201 offset:49152
	ds_read_b128 v[164:167], v201 offset:50176
	ds_read_b128 v[168:171], v201 offset:51200
	ds_read_b128 v[172:175], v201 offset:52224
	ds_read_b128 v[182:185], v201 offset:53248
	ds_read_b128 v[186:189], v201 offset:54272
	ds_read_b128 v[202:205], v201 offset:55296
	ds_read_b128 v[206:209], v201 offset:56320
	global_load_lds_dwordx4 v[210:211], off
	s_add_i32 m0, s10, 0x2000
	s_add_u32 s10, s50, 0xb0080
	v_lshl_add_u64 v[210:211], v[212:213], 0, s[60:61]
	s_addc_u32 s11, s51, 0
	s_add_i32 s25, s26, s23
	global_load_lds_dwordx4 v[210:211], off
	v_lshl_add_u64 v[210:211], s[10:11], 0, v[192:193]
	s_mov_b32 m0, s25
	s_nop 0
	global_load_lds_dwordx4 v[210:211], off
	v_lshl_add_u64 v[210:211], s[10:11], 0, v[176:177]
	s_add_i32 m0, s25, 0x2000
	s_nop 0
	global_load_lds_dwordx4 v[210:211], off
	v_lshl_add_u64 v[210:211], v[214:215], 0, s[60:61]
	s_mov_b32 m0, s79
	s_nop 0
	global_load_lds_dwordx4 v[210:211], off
	v_lshl_add_u64 v[210:211], v[216:217], 0, s[60:61]
	s_mov_b32 m0, s80
	s_nop 0
	global_load_lds_dwordx4 v[210:211], off
	s_waitcnt vmcnt(8)
	s_waitcnt lgkmcnt(0)
	s_barrier
	s_setprio 1
	v_mfma_f32_16x16x32_bf16 v[84:87], v[60:63], v[160:163], v[84:87]
	v_mfma_f32_16x16x32_bf16 v[56:59], v[68:71], v[160:163], v[56:59]
	v_mfma_f32_16x16x32_bf16 v[44:47], v[60:63], v[168:171], v[44:47]
	v_mfma_f32_16x16x32_bf16 v[40:43], v[68:71], v[168:171], v[40:43]
	v_mfma_f32_16x16x32_bf16 v[28:31], v[60:63], v[182:185], v[28:31]
	v_mfma_f32_16x16x32_bf16 v[24:27], v[68:71], v[182:185], v[24:27]
	v_mfma_f32_16x16x32_bf16 v[12:15], v[60:63], v[202:205], v[12:15]
	v_mfma_f32_16x16x32_bf16 v[8:11], v[68:71], v[202:205], v[8:11]
	v_mfma_f32_16x16x32_bf16 v[84:87], v[64:67], v[164:167], v[84:87]
	v_mfma_f32_16x16x32_bf16 v[56:59], v[72:75], v[164:167], v[56:59]
	v_mfma_f32_16x16x32_bf16 v[44:47], v[64:67], v[172:175], v[44:47]
	v_mfma_f32_16x16x32_bf16 v[40:43], v[72:75], v[172:175], v[40:43]
	v_mfma_f32_16x16x32_bf16 v[28:31], v[64:67], v[186:189], v[28:31]
	v_mfma_f32_16x16x32_bf16 v[24:27], v[72:75], v[186:189], v[24:27]
	v_mfma_f32_16x16x32_bf16 v[12:15], v[64:67], v[206:209], v[12:15]
	v_mfma_f32_16x16x32_bf16 v[8:11], v[72:75], v[206:209], v[8:11]
	s_setprio 0
	s_setprio 1
	v_mfma_f32_16x16x32_bf16 v[52:55], v[76:79], v[160:163], v[52:55]
	v_mfma_f32_16x16x32_bf16 v[48:51], v[88:91], v[160:163], v[48:51]
	v_mfma_f32_16x16x32_bf16 v[36:39], v[76:79], v[168:171], v[36:39]
	v_mfma_f32_16x16x32_bf16 v[32:35], v[88:91], v[168:171], v[32:35]
	v_mfma_f32_16x16x32_bf16 v[20:23], v[76:79], v[182:185], v[20:23]
	v_mfma_f32_16x16x32_bf16 v[16:19], v[88:91], v[182:185], v[16:19]
	v_mfma_f32_16x16x32_bf16 v[4:7], v[76:79], v[202:205], v[4:7]
	v_mfma_f32_16x16x32_bf16 v[0:3], v[88:91], v[202:205], v[0:3]
	v_mfma_f32_16x16x32_bf16 v[52:55], v[80:83], v[164:167], v[52:55]
	v_mfma_f32_16x16x32_bf16 v[48:51], v[92:95], v[164:167], v[48:51]
	v_mfma_f32_16x16x32_bf16 v[36:39], v[80:83], v[172:175], v[36:39]
	v_mfma_f32_16x16x32_bf16 v[32:35], v[92:95], v[172:175], v[32:35]
	v_mfma_f32_16x16x32_bf16 v[20:23], v[80:83], v[186:189], v[20:23]
	v_mfma_f32_16x16x32_bf16 v[16:19], v[92:95], v[186:189], v[16:19]
	v_mfma_f32_16x16x32_bf16 v[4:7], v[80:83], v[206:209], v[4:7]
	v_mfma_f32_16x16x32_bf16 v[0:3], v[92:95], v[206:209], v[0:3]
	s_setprio 0
	s_barrier
	s_add_i32 s24, s24, 2
	s_add_u32 s20, s20, 0x100
	s_addc_u32 s21, s21, 0
	s_cmp_gt_u32 s24, 41
	s_mov_b64 s[10:11], s[48:49]
	s_cbranch_scc0 .LBB0_347
	s_and_b64 vcc, exec, s[42:43]
	s_cbranch_vccz .LBB0_350
	s_barrier
